# next-ticket atomic of the decode queue collected behind the first task's page-table wait instead of a vmcnt(0) right after issue
# baseline (speedup 1.0000x reference)
; __device__ __forceinline__ void sb_decode_wave_loop(const Params& P, float* lds) {
;     ...
;     for (;;) {
;         const int t = __builtin_amdgcn_readfirstlane((int)nxt);
;         if (t >= DEC_NTASK) break;
;         if (lane == 0) nxt = atomicAdd(qd, 2u);
.LBB0_951:
	v_readfirstlane_b32 s34, v95
	s_cmpk_gt_i32 s34, 0x5fff
	s_mov_b64 s[0:1], -1
	s_cbranch_scc1 .LBB0_950
	s_and_saveexec_b64 s[0:1], s[4:5]
	s_cbranch_execz .LBB0_956
	s_mov_b64 s[36:37], exec
	v_mbcnt_lo_u32_b32 v2, s36, 0
	v_mbcnt_hi_u32_b32 v2, s37, v2
	v_cmp_eq_u32_e32 vcc, 0, v2
	s_and_saveexec_b64 s[2:3], vcc
	s_cbranch_execz .LBB0_955
	s_bcnt1_i32_b64 s33, s[36:37]
	s_lshl_b32 s33, s33, 1
	v_readlane_b32 s36, v252, 62
	v_mov_b32_e32 v3, s33
	v_readlane_b32 s37, v252, 63
	s_nop 4
	global_atomic_add v254, v83, v3, s[36:37] sc0

; __device__ __forceinline__ float bf2f(bf16_t b) { return __uint_as_float(((unsigned)b) << 16); }
; template <int NB>
; __device__ __forceinline__ void sb_decode_task(const Params& P, float* lds, int task) {
;     const int tid = threadIdx.x, lane = tid & 63, wave = tid >> 6;
;     const bf16_t* qb = (const bf16_t*)(P.ws + WS_QB);
;     float* dpart = (float*)(P.ws + WS_DPART); float* dl = (float*)(P.ws + WS_DL);
;     float* zl = lds + DEC_LDS_OFF / 4 + wave * 256; float* wl = zl + 128;
;     const int c = lane & 15, g = lane >> 4;
;     constexpr int NBT = 32 / NB;
;     const int h = task % SH, bj = task / SH, b = bj / NPAGES;
;     const int page = P.page_table[bj];
;     const float* Kp = P.cache_k + ((size_t)page * PAGE * SH + h) * HD + 4 * c;
;     const float* Vp = P.cache_v + ((size_t)page * PAGE * SH + h) * HD + 4 * c;
;     const bf16_t* qp = qb + (size_t)(NTOK + b) * SBW + h * 64 + 4 * c;
;     const float q0 = bf2f(qp[0]), q1 = bf2f(qp[1]), q2 = bf2f(qp[2]), q3 = bf2f(qp[3]);
;     const float bias = P.sb_bias[h] * LOG2E;
;     float4 cur[NB], nx[NB];
; #pragma unroll
;     for (int i = 0; i < NB; ++i) cur[i] = *(const float4*)(Kp + (size_t)(4 * i + g) * (SH * HD));
; #pragma unroll
;     for (int kb = 0; kb < NBT; ++kb) {
;         const float* np = (kb + 1 < NBT) ? Kp + (size_t)(4 * NB * (kb + 1)) * (SH * HD) : Vp;
; #pragma unroll
;         for (int i = 0; i < NB; ++i) nx[i] = *(const float4*)(np + (size_t)(4 * i + g) * (SH * HD));
; #pragma unroll
;         for (int i = 0; i < NB; ++i) { const int s = 4 * NB * kb + 4 * i + g;
;             float part = q0 * cur[i].x + q1 * cur[i].y + q2 * cur[i].z + q3 * cur[i].w; part = sum16(part);
;             if (c == 0) zl[s] = part + bias; }
; __device__ __forceinline__ void sb_decode_wave_loop(const Params& P, float* lds) {
;     ...
;     for (;;) {
;         const int t = __builtin_amdgcn_readfirstlane((int)nxt);
;         if (t >= DEC_NTASK) break;
;         if (lane == 0) nxt = atomicAdd(qd, 2u);
.LBB0_956:
	s_or_b64 exec, exec, s[0:1]
	v_readlane_b32 s36, v252, 48
	v_readlane_b32 s37, v252, 49
	s_mul_hi_i32 s1, s34, 0x2aaaaaab
	s_load_dwordx16 s[56:71], s[36:37], 0x0
	s_lshr_b32 s3, s1, 31
	s_add_i32 s0, s1, s3
	s_ashr_i32 s1, s1, 7
	s_mul_i32 s2, s0, 6
	s_add_i32 s33, s1, s3
	s_ashr_i32 s1, s0, 31
	s_sub_i32 s2, s34, s2
	s_lshl_b64 s[0:1], s[0:1], 2
	s_waitcnt lgkmcnt(0)
	s_add_u32 s0, s66, s0
	s_addc_u32 s1, s67, s1
	global_load_dword v2, v83, s[0:1]
	s_add_i32 s0, s33, 0x4000
	s_ashr_i32 s3, s2, 31
	s_mul_hi_i32 s1, s0, 0x300
	s_mulk_i32 s0, 0x300
	s_add_u32 s33, s38, s0
	s_addc_u32 s35, s39, s1
	s_lshl_b32 s0, s2, 6
	s_ashr_i32 s1, s0, 31
	s_lshl_b64 s[0:1], s[0:1], 1
	s_add_u32 s0, s33, s0
	s_addc_u32 s1, s35, s1
	v_readlane_b32 s56, v252, 16
	v_readlane_b32 s57, v252, 17
	v_readlane_b32 s64, v252, 24
	v_readlane_b32 s65, v252, 25
	s_mov_b64 s[56:57], s[64:65]
	v_mov_b32_e32 v91, v83
	v_readlane_b32 s58, v252, 18
	v_readlane_b32 s59, v252, 19
	v_readlane_b32 s60, v252, 20
	v_readlane_b32 s61, v252, 21
	v_readlane_b32 s62, v252, 22
	v_readlane_b32 s63, v252, 23
	v_readlane_b32 s66, v252, 26
	v_readlane_b32 s67, v252, 27
	v_readlane_b32 s68, v252, 28
	v_readlane_b32 s69, v252, 29
	v_readlane_b32 s70, v252, 30
	v_readlane_b32 s71, v252, 31
	s_waitcnt vmcnt(0)
	v_readfirstlane_b32 s101, v254
	v_mov_b32_e32 v253, v2
	s_nop 0
	v_mov_b32_e32 v95, s101
	v_mul_hi_i32 v3, v2, s42
	v_mul_lo_u32 v2, v2, s42
	v_lshl_add_u64 v[92:93], v[2:3], 0, s[2:3]
	v_lshlrev_b64 v[2:3], 8, v[92:93]
	v_lshl_add_u64 v[66:67], v[84:85], 0, v[2:3]
	global_load_dwordx2 v[2:3], v99, s[0:1]
	s_lshl_b64 s[0:1], s[2:3], 2
	s_add_u32 s0, s56, s0
	s_addc_u32 s1, s57, s1
	global_load_dword v22, v83, s[0:1]
	v_lshl_add_u64 v[18:19], v[66:67], 0, v[82:83]
	v_lshl_add_u64 v[20:21], v[66:67], 0, v[90:91]
	global_load_dwordx4 v[14:17], v[18:19], off nt
	global_load_dwordx4 v[62:65], v[20:21], off nt
	s_waitcnt vmcnt(3)
	v_lshlrev_b32_e32 v105, 16, v2
	v_and_b32_e32 v107, 0xffff0000, v2
	v_add_co_u32_e32 v2, vcc, s44, v18
	v_lshlrev_b32_e32 v106, 16, v3
	v_and_b32_e32 v104, 0xffff0000, v3
	v_addc_co_u32_e32 v3, vcc, 0, v19, vcc
	global_load_dwordx4 v[10:13], v[2:3], off offset:2048 nt
	v_add_co_u32_e32 v2, vcc, s45, v18
	s_waitcnt vmcnt(3)
	v_mul_f32_e32 v108, 0x3fb8aa3b, v22
	v_addc_co_u32_e32 v3, vcc, 0, v19, vcc
	global_load_dwordx4 v[6:9], v[2:3], off nt
	v_add_co_u32_e32 v2, vcc, s43, v18
	v_lshl_add_u64 v[22:23], v[66:67], 0, s[26:27]
	s_nop 0
	v_addc_co_u32_e32 v3, vcc, 0, v19, vcc
	v_add_co_u32_e32 v20, vcc, s46, v18
	v_lshl_add_u64 v[30:31], v[22:23], 0, v[82:83]
	s_nop 0
	v_addc_co_u32_e32 v21, vcc, 0, v19, vcc
	global_load_dwordx4 v[58:61], v[20:21], off offset:2048 nt
	v_add_co_u32_e32 v20, vcc, s47, v18
	v_lshl_add_u64 v[22:23], v[22:23], 0, v[90:91]
	s_nop 0
	v_addc_co_u32_e32 v21, vcc, 0, v19, vcc
	v_add_co_u32_e32 v18, vcc, s48, v18
	global_load_dwordx4 v[54:57], v[20:21], off nt
	s_nop 0
	v_addc_co_u32_e32 v19, vcc, 0, v19, vcc
	global_load_dwordx4 v[50:53], v[18:19], off offset:2048 nt
	v_add_co_u32_e32 v18, vcc, s44, v30
	global_load_dwordx4 v[22:25], v[22:23], off nt
	s_nop 0
	v_addc_co_u32_e32 v19, vcc, 0, v31, vcc
	global_load_dwordx4 v[34:37], v[18:19], off offset:2048 nt
	v_add_co_u32_e32 v18, vcc, s45, v30
	global_load_dwordx4 v[2:5], v[2:3], off offset:2048 nt
	s_nop 0
	v_addc_co_u32_e32 v19, vcc, 0, v31, vcc
	global_load_dwordx4 v[26:29], v[18:19], off nt
	v_add_co_u32_e32 v18, vcc, s43, v30
	global_load_dwordx4 v[46:49], v[30:31], off nt
	s_nop 0
	v_addc_co_u32_e32 v19, vcc, 0, v31, vcc
	v_add_co_u32_e32 v32, vcc, s46, v30
	global_load_dwordx4 v[18:21], v[18:19], off offset:2048 nt
	s_nop 0
	v_addc_co_u32_e32 v33, vcc, 0, v31, vcc
	global_load_dwordx4 v[38:41], v[32:33], off offset:2048 nt
	v_add_co_u32_e32 v32, vcc, s47, v30
	s_waitcnt vmcnt(13)
	v_mul_f32_e32 v15, v15, v107
	v_addc_co_u32_e32 v33, vcc, 0, v31, vcc
	v_add_co_u32_e32 v30, vcc, s48, v30
	global_load_dwordx4 v[42:45], v[32:33], off nt
	s_nop 0
	v_addc_co_u32_e32 v31, vcc, 0, v31, vcc
	global_load_dwordx4 v[30:33], v[30:31], off offset:2048 nt
	v_fmac_f32_e32 v15, v14, v105
	v_fmac_f32_e32 v15, v16, v106
	v_fmac_f32_e32 v15, v17, v104
	s_nop 1
	v_add_f32_dpp v14, v15, v15 quad_perm:[1,0,3,2] row_mask:0xf bank_mask:0xf bound_ctrl:1
	s_nop 1
	v_add_f32_dpp v14, v14, v14 quad_perm:[2,3,0,1] row_mask:0xf bank_mask:0xf bound_ctrl:1
	s_nop 1
	v_add_f32_dpp v14, v14, v14 row_ror:4 row_mask:0xf bank_mask:0xf bound_ctrl:1
	s_nop 1
	v_mov_b32_dpp v15, v14 row_ror:8 row_mask:0xf bank_mask:0xf bound_ctrl:1
	s_and_saveexec_b64 s[0:1], s[6:7]
	v_add_f32_e32 v14, v14, v15
	v_add_f32_e32 v14, v108, v14
	ds_write_b32 v96, v14
	s_or_b64 exec, exec, s[0:1]
	s_waitcnt vmcnt(13)
	v_mul_f32_e32 v11, v11, v107
	v_fmac_f32_e32 v11, v10, v105
	v_fmac_f32_e32 v11, v12, v106
	v_fmac_f32_e32 v11, v13, v104
	s_nop 1
	v_add_f32_dpp v10, v11, v11 quad_perm:[1,0,3,2] row_mask:0xf bank_mask:0xf bound_ctrl:1
	s_nop 1
	v_add_f32_dpp v10, v10, v10 quad_perm:[2,3,0,1] row_mask:0xf bank_mask:0xf bound_ctrl:1
	s_nop 1
	v_add_f32_dpp v10, v10, v10 row_ror:4 row_mask:0xf bank_mask:0xf bound_ctrl:1
	s_nop 1
	v_mov_b32_dpp v11, v10 row_ror:8 row_mask:0xf bank_mask:0xf bound_ctrl:1
	s_and_saveexec_b64 s[0:1], s[6:7]
	v_add_f32_e32 v10, v10, v11
	v_add_f32_e32 v10, v108, v10
	ds_write_b32 v96, v10 offset:16
	s_or_b64 exec, exec, s[0:1]
	s_waitcnt vmcnt(12)
; template <int NB>
; __device__ __forceinline__ void sb_decode_task(const Params& P, float* lds, int task) {
;     ...
;     for (int kb = 0; kb < NBT; ++kb) {
;         const float* np = (kb + 1 < NBT) ? Kp + (size_t)(4 * NB * (kb + 1)) * (SH * HD) : Vp;
; #pragma unroll
;         for (int i = 0; i < NB; ++i) nx[i] = *(const float4*)(np + (size_t)(4 * i + g) * (SH * HD));
; #pragma unroll
;         for (int i = 0; i < NB; ++i) { const int s = 4 * NB * kb + 4 * i + g;
;             float part = q0 * cur[i].x + q1 * cur[i].y + q2 * cur[i].z + q3 * cur[i].w; part = sum16(part);
;             if (c == 0) zl[s] = part + bias; }
	v_mul_f32_e32 v7, v7, v107
	v_fmac_f32_e32 v7, v6, v105
	v_fmac_f32_e32 v7, v8, v106
	v_fmac_f32_e32 v7, v9, v104
	s_nop 1
	v_add_f32_dpp v6, v7, v7 quad_perm:[1,0,3,2] row_mask:0xf bank_mask:0xf bound_ctrl:1
	s_nop 1
	v_add_f32_dpp v6, v6, v6 quad_perm:[2,3,0,1] row_mask:0xf bank_mask:0xf bound_ctrl:1
	s_nop 1
	v_add_f32_dpp v6, v6, v6 row_ror:4 row_mask:0xf bank_mask:0xf bound_ctrl:1
	s_nop 1
	v_mov_b32_dpp v7, v6 row_ror:8 row_mask:0xf bank_mask:0xf bound_ctrl:1
	s_and_saveexec_b64 s[0:1], s[6:7]
	v_add_f32_e32 v6, v6, v7
	v_add_f32_e32 v6, v108, v6
	ds_write_b32 v96, v6 offset:32
	s_or_b64 exec, exec, s[0:1]
	s_waitcnt vmcnt(6)
	v_mul_f32_e32 v3, v3, v107
	v_fmac_f32_e32 v3, v2, v105
	v_fmac_f32_e32 v3, v4, v106
	v_fmac_f32_e32 v3, v5, v104
	s_nop 1
	v_add_f32_dpp v2, v3, v3 quad_perm:[1,0,3,2] row_mask:0xf bank_mask:0xf bound_ctrl:1
	s_nop 1
	v_add_f32_dpp v2, v2, v2 quad_perm:[2,3,0,1] row_mask:0xf bank_mask:0xf bound_ctrl:1
	s_nop 1
	v_add_f32_dpp v2, v2, v2 row_ror:4 row_mask:0xf bank_mask:0xf bound_ctrl:1
	s_nop 1
	v_mov_b32_dpp v3, v2 row_ror:8 row_mask:0xf bank_mask:0xf bound_ctrl:1
	s_and_saveexec_b64 s[0:1], s[6:7]
	v_add_f32_e32 v2, v2, v3
	v_add_f32_e32 v2, v108, v2
	ds_write_b32 v96, v2 offset:48
	s_or_b64 exec, exec, s[0:1]
	v_mul_f32_e32 v2, v63, v107
	v_fmac_f32_e32 v2, v62, v105
	v_fmac_f32_e32 v2, v64, v106
	v_fmac_f32_e32 v2, v65, v104
	s_nop 1
	v_add_f32_dpp v2, v2, v2 quad_perm:[1,0,3,2] row_mask:0xf bank_mask:0xf bound_ctrl:1
	s_nop 1
	v_add_f32_dpp v2, v2, v2 quad_perm:[2,3,0,1] row_mask:0xf bank_mask:0xf bound_ctrl:1
	s_nop 1
	v_add_f32_dpp v2, v2, v2 row_ror:4 row_mask:0xf bank_mask:0xf bound_ctrl:1
	s_nop 1
	v_mov_b32_dpp v3, v2 row_ror:8 row_mask:0xf bank_mask:0xf bound_ctrl:1
	s_and_saveexec_b64 s[0:1], s[6:7]
	v_add_f32_e32 v2, v2, v3
	v_add_f32_e32 v2, v108, v2
	ds_write_b32 v96, v2 offset:64
	s_or_b64 exec, exec, s[0:1]
	v_mul_f32_e32 v2, v59, v107
	v_fmac_f32_e32 v2, v58, v105
	v_fmac_f32_e32 v2, v60, v106
	v_fmac_f32_e32 v2, v61, v104
	s_nop 1
	v_add_f32_dpp v2, v2, v2 quad_perm:[1,0,3,2] row_mask:0xf bank_mask:0xf bound_ctrl:1
	s_nop 1
	v_add_f32_dpp v2, v2, v2 quad_perm:[2,3,0,1] row_mask:0xf bank_mask:0xf bound_ctrl:1
	s_nop 1
	v_add_f32_dpp v2, v2, v2 row_ror:4 row_mask:0xf bank_mask:0xf bound_ctrl:1
	s_nop 1
	v_mov_b32_dpp v3, v2 row_ror:8 row_mask:0xf bank_mask:0xf bound_ctrl:1
	s_and_saveexec_b64 s[0:1], s[6:7]
	v_add_f32_e32 v2, v2, v3
	v_add_f32_e32 v2, v108, v2
	ds_write_b32 v96, v2 offset:80
	s_or_b64 exec, exec, s[0:1]
	v_mul_f32_e32 v2, v55, v107
	v_fmac_f32_e32 v2, v54, v105
	v_fmac_f32_e32 v2, v56, v106
	v_fmac_f32_e32 v2, v57, v104
	s_nop 1
	v_add_f32_dpp v2, v2, v2 quad_perm:[1,0,3,2] row_mask:0xf bank_mask:0xf bound_ctrl:1
	s_nop 1
	v_add_f32_dpp v2, v2, v2 quad_perm:[2,3,0,1] row_mask:0xf bank_mask:0xf bound_ctrl:1
	s_nop 1
	v_add_f32_dpp v2, v2, v2 row_ror:4 row_mask:0xf bank_mask:0xf bound_ctrl:1
	s_nop 1
	v_mov_b32_dpp v3, v2 row_ror:8 row_mask:0xf bank_mask:0xf bound_ctrl:1
	s_and_saveexec_b64 s[0:1], s[6:7]
	v_add_f32_e32 v2, v2, v3
	v_add_f32_e32 v2, v108, v2
	ds_write_b32 v96, v2 offset:96
	s_or_b64 exec, exec, s[0:1]
	v_mul_f32_e32 v2, v51, v107
	v_fmac_f32_e32 v2, v50, v105
	v_fmac_f32_e32 v2, v52, v106
	v_fmac_f32_e32 v2, v53, v104
	s_nop 1
	v_add_f32_dpp v2, v2, v2 quad_perm:[1,0,3,2] row_mask:0xf bank_mask:0xf bound_ctrl:1
	s_nop 1
	v_add_f32_dpp v2, v2, v2 quad_perm:[2,3,0,1] row_mask:0xf bank_mask:0xf bound_ctrl:1
	s_nop 1
	v_add_f32_dpp v2, v2, v2 row_ror:4 row_mask:0xf bank_mask:0xf bound_ctrl:1
	s_nop 1
	v_mov_b32_dpp v3, v2 row_ror:8 row_mask:0xf bank_mask:0xf bound_ctrl:1
	s_and_saveexec_b64 s[0:1], s[6:7]
	v_add_f32_e32 v2, v2, v3
	v_add_f32_e32 v2, v108, v2
	ds_write_b32 v96, v2 offset:112
	s_or_b64 exec, exec, s[0:1]
	v_lshl_add_u64 v[2:3], v[66:67], 0, s[28:29]
	v_lshl_add_u64 v[4:5], v[2:3], 0, v[82:83]
	v_add_co_u32_e32 v6, vcc, 0x1000, v4
	v_mov_b32_e32 v91, v83
	s_nop 0
	v_addc_co_u32_e32 v7, vcc, 0, v5, vcc
	global_load_dwordx4 v[78:81], v[4:5], off nt
	global_load_dwordx4 v[70:73], v[6:7], off offset:2048 nt
	v_add_co_u32_e32 v6, vcc, 0x3000, v4
	v_lshl_add_u64 v[2:3], v[2:3], 0, v[90:91]
	s_nop 0
	v_addc_co_u32_e32 v7, vcc, 0, v5, vcc
	v_add_co_u32_e32 v8, vcc, s43, v4
	s_waitcnt vmcnt(6)
	v_mul_f32_e32 v47, v47, v107
	v_addc_co_u32_e32 v9, vcc, 0, v5, vcc
	global_load_dwordx4 v[62:65], v[6:7], off nt
	global_load_dwordx4 v[54:57], v[8:9], off offset:2048 nt
	v_add_co_u32_e32 v6, vcc, 0x7000, v4
	v_fmac_f32_e32 v47, v46, v105
	s_nop 0
	v_addc_co_u32_e32 v7, vcc, 0, v5, vcc
	global_load_dwordx4 v[14:17], v[2:3], off nt
	global_load_dwordx4 v[10:13], v[6:7], off offset:2048 nt
	v_add_co_u32_e32 v2, vcc, 0x9000, v4
	v_fmac_f32_e32 v47, v48, v106
	s_nop 0
	v_addc_co_u32_e32 v3, vcc, 0, v5, vcc
	v_add_co_u32_e32 v4, vcc, 0xa000, v4
	v_fmac_f32_e32 v47, v49, v104
	s_nop 0
	v_addc_co_u32_e32 v5, vcc, 0, v5, vcc
	global_load_dwordx4 v[6:9], v[2:3], off nt
	s_nop 0
	global_load_dwordx4 v[2:5], v[4:5], off offset:2048 nt
	v_add_f32_dpp v46, v47, v47 quad_perm:[1,0,3,2] row_mask:0xf bank_mask:0xf bound_ctrl:1
	s_nop 1
	v_add_f32_dpp v46, v46, v46 quad_perm:[2,3,0,1] row_mask:0xf bank_mask:0xf bound_ctrl:1
	s_nop 1
	v_add_f32_dpp v46, v46, v46 row_ror:4 row_mask:0xf bank_mask:0xf bound_ctrl:1
	s_nop 1
	v_mov_b32_dpp v47, v46 row_ror:8 row_mask:0xf bank_mask:0xf bound_ctrl:1
	s_and_saveexec_b64 s[0:1], s[6:7]
	v_add_f32_e32 v46, v46, v47
	v_add_f32_e32 v46, v108, v46
	ds_write_b32 v96, v46 offset:128
	s_or_b64 exec, exec, s[0:1]
	v_mul_f32_e32 v35, v35, v107
	v_fmac_f32_e32 v35, v34, v105
	v_fmac_f32_e32 v35, v36, v106
	v_fmac_f32_e32 v35, v37, v104
	s_nop 1
	v_add_f32_dpp v34, v35, v35 quad_perm:[1,0,3,2] row_mask:0xf bank_mask:0xf bound_ctrl:1
	s_nop 1
	v_add_f32_dpp v34, v34, v34 quad_perm:[2,3,0,1] row_mask:0xf bank_mask:0xf bound_ctrl:1
	s_nop 1
	v_add_f32_dpp v34, v34, v34 row_ror:4 row_mask:0xf bank_mask:0xf bound_ctrl:1
	s_nop 1
	v_mov_b32_dpp v35, v34 row_ror:8 row_mask:0xf bank_mask:0xf bound_ctrl:1
	s_and_saveexec_b64 s[0:1], s[6:7]
	v_add_f32_e32 v34, v34, v35
	v_add_f32_e32 v34, v108, v34
	ds_write_b32 v96, v34 offset:144
	s_or_b64 exec, exec, s[0:1]
	v_mul_f32_e32 v27, v27, v107
	v_fmac_f32_e32 v27, v26, v105
	v_fmac_f32_e32 v27, v28, v106
	v_fmac_f32_e32 v27, v29, v104
	s_nop 1
	v_add_f32_dpp v26, v27, v27 quad_perm:[1,0,3,2] row_mask:0xf bank_mask:0xf bound_ctrl:1
	s_nop 1
	v_add_f32_dpp v26, v26, v26 quad_perm:[2,3,0,1] row_mask:0xf bank_mask:0xf bound_ctrl:1
	s_nop 1
	v_add_f32_dpp v26, v26, v26 row_ror:4 row_mask:0xf bank_mask:0xf bound_ctrl:1
	s_nop 1
	v_mov_b32_dpp v27, v26 row_ror:8 row_mask:0xf bank_mask:0xf bound_ctrl:1
	s_and_saveexec_b64 s[0:1], s[6:7]
	v_add_f32_e32 v26, v26, v27
	v_add_f32_e32 v26, v108, v26
	ds_write_b32 v96, v26 offset:160
	s_or_b64 exec, exec, s[0:1]
	s_waitcnt vmcnt(11)
; template <int NB>
; __device__ __forceinline__ void sb_decode_task(const Params& P, float* lds, int task) {
;     ...
;     for (int kb = 0; kb < NBT; ++kb) {
;         const float* np = (kb + 1 < NBT) ? Kp + (size_t)(4 * NB * (kb + 1)) * (SH * HD) : Vp;
; #pragma unroll
;         for (int i = 0; i < NB; ++i) nx[i] = *(const float4*)(np + (size_t)(4 * i + g) * (SH * HD));
; #pragma unroll
;         for (int i = 0; i < NB; ++i) { const int s = 4 * NB * kb + 4 * i + g;
;             float part = q0 * cur[i].x + q1 * cur[i].y + q2 * cur[i].z + q3 * cur[i].w; part = sum16(part);
;             if (c == 0) zl[s] = part + bias; }
	v_mul_f32_e32 v19, v19, v107
	v_fmac_f32_e32 v19, v18, v105
	v_fmac_f32_e32 v19, v20, v106
	v_fmac_f32_e32 v19, v21, v104
	s_nop 1
	v_add_f32_dpp v18, v19, v19 quad_perm:[1,0,3,2] row_mask:0xf bank_mask:0xf bound_ctrl:1
	s_nop 1
	v_add_f32_dpp v18, v18, v18 quad_perm:[2,3,0,1] row_mask:0xf bank_mask:0xf bound_ctrl:1
	s_nop 1
	v_add_f32_dpp v18, v18, v18 row_ror:4 row_mask:0xf bank_mask:0xf bound_ctrl:1
	s_nop 1
	v_mov_b32_dpp v19, v18 row_ror:8 row_mask:0xf bank_mask:0xf bound_ctrl:1
	s_and_saveexec_b64 s[0:1], s[6:7]
	v_add_f32_e32 v18, v18, v19
	v_add_f32_e32 v18, v108, v18
	ds_write_b32 v96, v18 offset:176
	s_or_b64 exec, exec, s[0:1]
	v_mul_f32_e32 v18, v23, v107
	v_fmac_f32_e32 v18, v22, v105
	v_fmac_f32_e32 v18, v24, v106
	v_fmac_f32_e32 v18, v25, v104
	s_nop 1
	v_add_f32_dpp v18, v18, v18 quad_perm:[1,0,3,2] row_mask:0xf bank_mask:0xf bound_ctrl:1
	s_nop 1
	v_add_f32_dpp v18, v18, v18 quad_perm:[2,3,0,1] row_mask:0xf bank_mask:0xf bound_ctrl:1
	s_nop 1
	v_add_f32_dpp v18, v18, v18 row_ror:4 row_mask:0xf bank_mask:0xf bound_ctrl:1
	s_nop 1
	v_mov_b32_dpp v19, v18 row_ror:8 row_mask:0xf bank_mask:0xf bound_ctrl:1
	s_and_saveexec_b64 s[0:1], s[6:7]
	v_add_f32_e32 v18, v18, v19
	v_add_f32_e32 v18, v108, v18
	ds_write_b32 v96, v18 offset:192
	s_or_b64 exec, exec, s[0:1]
	s_waitcnt vmcnt(10)
	v_mul_f32_e32 v18, v39, v107
	v_fmac_f32_e32 v18, v38, v105
	v_fmac_f32_e32 v18, v40, v106
	v_fmac_f32_e32 v18, v41, v104
	s_nop 1
	v_add_f32_dpp v18, v18, v18 quad_perm:[1,0,3,2] row_mask:0xf bank_mask:0xf bound_ctrl:1
	s_nop 1
	v_add_f32_dpp v18, v18, v18 quad_perm:[2,3,0,1] row_mask:0xf bank_mask:0xf bound_ctrl:1
	s_nop 1
	v_add_f32_dpp v18, v18, v18 row_ror:4 row_mask:0xf bank_mask:0xf bound_ctrl:1
	s_nop 1
	v_mov_b32_dpp v19, v18 row_ror:8 row_mask:0xf bank_mask:0xf bound_ctrl:1
	s_and_saveexec_b64 s[0:1], s[6:7]
	v_add_f32_e32 v18, v18, v19
	v_add_f32_e32 v18, v108, v18
	ds_write_b32 v96, v18 offset:208
	s_or_b64 exec, exec, s[0:1]
	s_waitcnt vmcnt(9)
	v_mul_f32_e32 v18, v43, v107
	v_fmac_f32_e32 v18, v42, v105
	v_fmac_f32_e32 v18, v44, v106
	v_fmac_f32_e32 v18, v45, v104
	s_nop 1
	v_add_f32_dpp v18, v18, v18 quad_perm:[1,0,3,2] row_mask:0xf bank_mask:0xf bound_ctrl:1
	s_nop 1
	v_add_f32_dpp v18, v18, v18 quad_perm:[2,3,0,1] row_mask:0xf bank_mask:0xf bound_ctrl:1
	s_nop 1
	v_add_f32_dpp v18, v18, v18 row_ror:4 row_mask:0xf bank_mask:0xf bound_ctrl:1
	s_nop 1
	v_mov_b32_dpp v19, v18 row_ror:8 row_mask:0xf bank_mask:0xf bound_ctrl:1
	s_and_saveexec_b64 s[0:1], s[6:7]
	v_add_f32_e32 v18, v18, v19
	v_add_f32_e32 v18, v108, v18
	ds_write_b32 v96, v18 offset:224
	s_or_b64 exec, exec, s[0:1]
	s_waitcnt vmcnt(8)
	v_mul_f32_e32 v18, v31, v107
	v_fmac_f32_e32 v18, v30, v105
	v_fmac_f32_e32 v18, v32, v106
	v_fmac_f32_e32 v18, v33, v104
	s_nop 1
	v_add_f32_dpp v18, v18, v18 quad_perm:[1,0,3,2] row_mask:0xf bank_mask:0xf bound_ctrl:1
	s_nop 1
	v_add_f32_dpp v18, v18, v18 quad_perm:[2,3,0,1] row_mask:0xf bank_mask:0xf bound_ctrl:1
	s_nop 1
	v_add_f32_dpp v18, v18, v18 row_ror:4 row_mask:0xf bank_mask:0xf bound_ctrl:1
	s_nop 1
	v_mov_b32_dpp v19, v18 row_ror:8 row_mask:0xf bank_mask:0xf bound_ctrl:1
	s_and_saveexec_b64 s[0:1], s[6:7]
	v_add_f32_e32 v18, v18, v19
	v_add_f32_e32 v18, v108, v18
	ds_write_b32 v96, v18 offset:240
	s_or_b64 exec, exec, s[0:1]
	v_lshl_add_u64 v[18:19], v[66:67], 0, s[30:31]
	v_lshl_add_u64 v[20:21], v[18:19], 0, v[82:83]
	v_add_co_u32_e32 v22, vcc, 0x1000, v20
	v_mov_b32_e32 v91, v83
	s_nop 0
	v_addc_co_u32_e32 v23, vcc, 0, v21, vcc
	global_load_dwordx4 v[74:77], v[20:21], off nt
	global_load_dwordx4 v[66:69], v[22:23], off offset:2048 nt
	v_add_co_u32_e32 v22, vcc, 0x3000, v20
	v_lshl_add_u64 v[18:19], v[18:19], 0, v[90:91]
	s_nop 0
	v_addc_co_u32_e32 v23, vcc, 0, v21, vcc
	v_add_co_u32_e32 v24, vcc, s43, v20
	s_nop 1
	v_addc_co_u32_e32 v25, vcc, 0, v21, vcc
	global_load_dwordx4 v[58:61], v[22:23], off nt
	global_load_dwordx4 v[50:53], v[24:25], off offset:2048 nt
	v_add_co_u32_e32 v22, vcc, 0x7000, v20
	s_nop 1
	v_addc_co_u32_e32 v23, vcc, 0, v21, vcc
	global_load_dwordx4 v[46:49], v[18:19], off nt
	global_load_dwordx4 v[42:45], v[22:23], off offset:2048 nt
	v_add_co_u32_e32 v18, vcc, 0x9000, v20
	s_nop 1
	v_addc_co_u32_e32 v19, vcc, 0, v21, vcc
	v_add_co_u32_e32 v20, vcc, 0xa000, v20
	s_nop 1
	v_addc_co_u32_e32 v21, vcc, 0, v21, vcc
	global_load_dwordx4 v[38:41], v[18:19], off nt
	global_load_dwordx4 v[34:37], v[20:21], off offset:2048 nt
	s_waitcnt vmcnt(15)
	v_mul_f32_e32 v18, v79, v107
	v_fmac_f32_e32 v18, v78, v105
	v_fmac_f32_e32 v18, v80, v106
	v_fmac_f32_e32 v18, v81, v104
	s_nop 1
	v_add_f32_dpp v18, v18, v18 quad_perm:[1,0,3,2] row_mask:0xf bank_mask:0xf bound_ctrl:1
	s_nop 1
	v_add_f32_dpp v18, v18, v18 quad_perm:[2,3,0,1] row_mask:0xf bank_mask:0xf bound_ctrl:1
	s_nop 1
	v_add_f32_dpp v18, v18, v18 row_ror:4 row_mask:0xf bank_mask:0xf bound_ctrl:1
	s_nop 1
	v_mov_b32_dpp v19, v18 row_ror:8 row_mask:0xf bank_mask:0xf bound_ctrl:1
	s_and_saveexec_b64 s[0:1], s[6:7]
	v_add_f32_e32 v18, v18, v19
	v_add_f32_e32 v18, v108, v18
	ds_write_b32 v96, v18 offset:256
	s_or_b64 exec, exec, s[0:1]
	s_waitcnt vmcnt(14)
	v_mul_f32_e32 v18, v71, v107
	v_fmac_f32_e32 v18, v70, v105
	v_fmac_f32_e32 v18, v72, v106
	v_fmac_f32_e32 v18, v73, v104
	s_nop 1
	v_add_f32_dpp v18, v18, v18 quad_perm:[1,0,3,2] row_mask:0xf bank_mask:0xf bound_ctrl:1
	s_nop 1
	v_add_f32_dpp v18, v18, v18 quad_perm:[2,3,0,1] row_mask:0xf bank_mask:0xf bound_ctrl:1
	s_nop 1
	v_add_f32_dpp v18, v18, v18 row_ror:4 row_mask:0xf bank_mask:0xf bound_ctrl:1
	s_nop 1
	v_mov_b32_dpp v19, v18 row_ror:8 row_mask:0xf bank_mask:0xf bound_ctrl:1
	s_and_saveexec_b64 s[0:1], s[6:7]
	v_add_f32_e32 v18, v18, v19
	v_add_f32_e32 v18, v108, v18
	ds_write_b32 v96, v18 offset:272
	s_or_b64 exec, exec, s[0:1]
	s_waitcnt vmcnt(13)
; template <int NB>
; __device__ __forceinline__ void sb_decode_task(const Params& P, float* lds, int task) {
;     ...
;     for (int kb = 0; kb < NBT; ++kb) {
;         const float* np = (kb + 1 < NBT) ? Kp + (size_t)(4 * NB * (kb + 1)) * (SH * HD) : Vp;
; #pragma unroll
;         for (int i = 0; i < NB; ++i) nx[i] = *(const float4*)(np + (size_t)(4 * i + g) * (SH * HD));
; #pragma unroll
;         for (int i = 0; i < NB; ++i) { const int s = 4 * NB * kb + 4 * i + g;
;             float part = q0 * cur[i].x + q1 * cur[i].y + q2 * cur[i].z + q3 * cur[i].w; part = sum16(part);
;             if (c == 0) zl[s] = part + bias; }
	v_mul_f32_e32 v18, v63, v107
	v_fmac_f32_e32 v18, v62, v105
	v_fmac_f32_e32 v18, v64, v106
	v_fmac_f32_e32 v18, v65, v104
	s_nop 1
	v_add_f32_dpp v18, v18, v18 quad_perm:[1,0,3,2] row_mask:0xf bank_mask:0xf bound_ctrl:1
	s_nop 1
	v_add_f32_dpp v18, v18, v18 quad_perm:[2,3,0,1] row_mask:0xf bank_mask:0xf bound_ctrl:1
	s_nop 1
	v_add_f32_dpp v18, v18, v18 row_ror:4 row_mask:0xf bank_mask:0xf bound_ctrl:1
	s_nop 1
	v_mov_b32_dpp v19, v18 row_ror:8 row_mask:0xf bank_mask:0xf bound_ctrl:1
	s_and_saveexec_b64 s[0:1], s[6:7]
	v_add_f32_e32 v18, v18, v19
	v_add_f32_e32 v18, v108, v18
	ds_write_b32 v96, v18 offset:288
	s_or_b64 exec, exec, s[0:1]
	s_waitcnt vmcnt(12)
	v_mul_f32_e32 v18, v55, v107
	v_fmac_f32_e32 v18, v54, v105
	v_fmac_f32_e32 v18, v56, v106
	v_fmac_f32_e32 v18, v57, v104
	s_nop 1
	v_add_f32_dpp v18, v18, v18 quad_perm:[1,0,3,2] row_mask:0xf bank_mask:0xf bound_ctrl:1
	s_nop 1
	v_add_f32_dpp v18, v18, v18 quad_perm:[2,3,0,1] row_mask:0xf bank_mask:0xf bound_ctrl:1
	s_nop 1
	v_add_f32_dpp v18, v18, v18 row_ror:4 row_mask:0xf bank_mask:0xf bound_ctrl:1
	s_nop 1
	v_mov_b32_dpp v19, v18 row_ror:8 row_mask:0xf bank_mask:0xf bound_ctrl:1
	s_and_saveexec_b64 s[0:1], s[6:7]
	v_add_f32_e32 v18, v18, v19
	v_add_f32_e32 v18, v108, v18
	ds_write_b32 v96, v18 offset:304
	s_or_b64 exec, exec, s[0:1]
	s_waitcnt vmcnt(11)
	v_mul_f32_e32 v15, v15, v107
	v_fmac_f32_e32 v15, v14, v105
	v_fmac_f32_e32 v15, v16, v106
	v_fmac_f32_e32 v15, v17, v104
	s_nop 1
	v_add_f32_dpp v14, v15, v15 quad_perm:[1,0,3,2] row_mask:0xf bank_mask:0xf bound_ctrl:1
	s_nop 1
	v_add_f32_dpp v14, v14, v14 quad_perm:[2,3,0,1] row_mask:0xf bank_mask:0xf bound_ctrl:1
	s_nop 1
	v_add_f32_dpp v14, v14, v14 row_ror:4 row_mask:0xf bank_mask:0xf bound_ctrl:1
	s_nop 1
	v_mov_b32_dpp v15, v14 row_ror:8 row_mask:0xf bank_mask:0xf bound_ctrl:1
	s_and_saveexec_b64 s[0:1], s[6:7]
	v_add_f32_e32 v14, v14, v15
	v_add_f32_e32 v14, v108, v14
	ds_write_b32 v96, v14 offset:320
	s_or_b64 exec, exec, s[0:1]
	s_waitcnt vmcnt(10)
	v_mul_f32_e32 v11, v11, v107
	v_fmac_f32_e32 v11, v10, v105
	v_fmac_f32_e32 v11, v12, v106
	v_fmac_f32_e32 v11, v13, v104
	s_nop 1
	v_add_f32_dpp v10, v11, v11 quad_perm:[1,0,3,2] row_mask:0xf bank_mask:0xf bound_ctrl:1
	s_nop 1
	v_add_f32_dpp v10, v10, v10 quad_perm:[2,3,0,1] row_mask:0xf bank_mask:0xf bound_ctrl:1
	s_nop 1
	v_add_f32_dpp v10, v10, v10 row_ror:4 row_mask:0xf bank_mask:0xf bound_ctrl:1
	s_nop 1
	v_mov_b32_dpp v11, v10 row_ror:8 row_mask:0xf bank_mask:0xf bound_ctrl:1
	s_and_saveexec_b64 s[0:1], s[6:7]
	v_add_f32_e32 v10, v10, v11
	v_add_f32_e32 v10, v108, v10
	ds_write_b32 v96, v10 offset:336
	s_or_b64 exec, exec, s[0:1]
	s_waitcnt vmcnt(9)
	v_mul_f32_e32 v7, v7, v107
	v_fmac_f32_e32 v7, v6, v105
	v_fmac_f32_e32 v7, v8, v106
	v_fmac_f32_e32 v7, v9, v104
	s_nop 1
	v_add_f32_dpp v6, v7, v7 quad_perm:[1,0,3,2] row_mask:0xf bank_mask:0xf bound_ctrl:1
	s_nop 1
	v_add_f32_dpp v6, v6, v6 quad_perm:[2,3,0,1] row_mask:0xf bank_mask:0xf bound_ctrl:1
	s_nop 1
	v_add_f32_dpp v6, v6, v6 row_ror:4 row_mask:0xf bank_mask:0xf bound_ctrl:1
	s_nop 1
	v_mov_b32_dpp v7, v6 row_ror:8 row_mask:0xf bank_mask:0xf bound_ctrl:1
	s_and_saveexec_b64 s[0:1], s[6:7]
	v_add_f32_e32 v6, v6, v7
	v_add_f32_e32 v6, v108, v6
	ds_write_b32 v96, v6 offset:352
	s_or_b64 exec, exec, s[0:1]
	s_waitcnt vmcnt(8)
	v_mul_f32_e32 v3, v3, v107
	v_fmac_f32_e32 v3, v2, v105
	v_fmac_f32_e32 v3, v4, v106
	v_fmac_f32_e32 v3, v5, v104
	s_nop 1
	v_add_f32_dpp v2, v3, v3 quad_perm:[1,0,3,2] row_mask:0xf bank_mask:0xf bound_ctrl:1
	s_nop 1
	v_add_f32_dpp v2, v2, v2 quad_perm:[2,3,0,1] row_mask:0xf bank_mask:0xf bound_ctrl:1
	s_nop 1
	v_add_f32_dpp v2, v2, v2 row_ror:4 row_mask:0xf bank_mask:0xf bound_ctrl:1
	s_nop 1
	v_mov_b32_dpp v3, v2 row_ror:8 row_mask:0xf bank_mask:0xf bound_ctrl:1
	s_and_saveexec_b64 s[0:1], s[6:7]
	v_add_f32_e32 v2, v2, v3
	v_add_f32_e32 v2, v108, v2
	ds_write_b32 v96, v2 offset:368
	s_or_b64 exec, exec, s[0:1]
	v_lshlrev_b64 v[2:3], 6, v[92:93]
	v_lshl_add_u64 v[6:7], v[2:3], 2, v[86:87]
	v_lshl_add_u64 v[54:55], v[6:7], 0, v[82:83]
	v_add_co_u32_e32 v2, vcc, 0x1000, v54
	v_mov_b32_e32 v91, v83
	s_nop 0
	v_addc_co_u32_e32 v3, vcc, 0, v55, vcc
	v_add_co_u32_e32 v8, vcc, 0x3000, v54
	v_lshl_add_u64 v[10:11], v[6:7], 0, v[90:91]
	s_nop 0
	v_addc_co_u32_e32 v9, vcc, 0, v55, vcc
	v_add_co_u32_e32 v14, vcc, s43, v54
	global_load_dwordx4 v[30:33], v[54:55], off nt
	s_nop 0
	global_load_dwordx4 v[2:5], v[2:3], off offset:2048 nt
	v_addc_co_u32_e32 v15, vcc, 0, v55, vcc
	v_add_co_u32_e32 v18, vcc, 0x7000, v54
	global_load_dwordx4 v[6:9], v[8:9], off nt
	s_nop 0
	global_load_dwordx4 v[10:13], v[10:11], off nt
	v_addc_co_u32_e32 v19, vcc, 0, v55, vcc
	v_add_co_u32_e32 v22, vcc, 0x9000, v54
	global_load_dwordx4 v[14:17], v[14:15], off offset:2048 nt
	s_nop 0
	global_load_dwordx4 v[18:21], v[18:19], off offset:2048 nt
	v_addc_co_u32_e32 v23, vcc, 0, v55, vcc
	v_add_co_u32_e32 v26, vcc, 0xa000, v54
	s_waitcnt vmcnt(13)
	v_mul_f32_e32 v56, v75, v107
	v_addc_co_u32_e32 v27, vcc, 0, v55, vcc
	global_load_dwordx4 v[22:25], v[22:23], off nt
	s_nop 0
	global_load_dwordx4 v[26:29], v[26:27], off offset:2048 nt
	v_fmac_f32_e32 v56, v74, v105
	v_fmac_f32_e32 v56, v76, v106
	v_fmac_f32_e32 v56, v77, v104
	s_nop 1
	v_add_f32_dpp v56, v56, v56 quad_perm:[1,0,3,2] row_mask:0xf bank_mask:0xf bound_ctrl:1
	s_nop 1
	v_add_f32_dpp v56, v56, v56 quad_perm:[2,3,0,1] row_mask:0xf bank_mask:0xf bound_ctrl:1
	s_nop 1
	v_add_f32_dpp v56, v56, v56 row_ror:4 row_mask:0xf bank_mask:0xf bound_ctrl:1
	s_nop 1
	v_mov_b32_dpp v57, v56 row_ror:8 row_mask:0xf bank_mask:0xf bound_ctrl:1
	s_and_saveexec_b64 s[0:1], s[6:7]
	v_add_f32_e32 v56, v56, v57
	v_add_f32_e32 v56, v108, v56
	ds_write_b32 v96, v56 offset:384
	s_or_b64 exec, exec, s[0:1]
	s_waitcnt vmcnt(14)
; template <int NB>
; __device__ __forceinline__ void sb_decode_task(const Params& P, float* lds, int task) {
;     ...
;     for (int kb = 0; kb < NBT; ++kb) {
;         const float* np = (kb + 1 < NBT) ? Kp + (size_t)(4 * NB * (kb + 1)) * (SH * HD) : Vp;
; #pragma unroll
;         for (int i = 0; i < NB; ++i) nx[i] = *(const float4*)(np + (size_t)(4 * i + g) * (SH * HD));
; #pragma unroll
;         for (int i = 0; i < NB; ++i) { const int s = 4 * NB * kb + 4 * i + g;
;             float part = q0 * cur[i].x + q1 * cur[i].y + q2 * cur[i].z + q3 * cur[i].w; part = sum16(part);
;             if (c == 0) zl[s] = part + bias; }
; #pragma unroll
;         for (int i = 0; i < NB; ++i) cur[i] = nx[i];
;     }
;     asm volatile("s_waitcnt lgkmcnt(0)" ::: "memory");
;     __builtin_amdgcn_wave_barrier();
;     const float z0 = zl[2 * lane], z1 = zl[2 * lane + 1];
	v_mul_f32_e32 v56, v67, v107
	v_fmac_f32_e32 v56, v66, v105
	v_fmac_f32_e32 v56, v68, v106
	v_fmac_f32_e32 v56, v69, v104
	s_nop 1
	v_add_f32_dpp v56, v56, v56 quad_perm:[1,0,3,2] row_mask:0xf bank_mask:0xf bound_ctrl:1
	s_nop 1
	v_add_f32_dpp v56, v56, v56 quad_perm:[2,3,0,1] row_mask:0xf bank_mask:0xf bound_ctrl:1
	s_nop 1
	v_add_f32_dpp v56, v56, v56 row_ror:4 row_mask:0xf bank_mask:0xf bound_ctrl:1
	s_nop 1
	v_mov_b32_dpp v57, v56 row_ror:8 row_mask:0xf bank_mask:0xf bound_ctrl:1
	s_and_saveexec_b64 s[0:1], s[6:7]
	v_add_f32_e32 v56, v56, v57
	v_add_f32_e32 v56, v108, v56
	ds_write_b32 v96, v56 offset:400
	s_or_b64 exec, exec, s[0:1]
	s_waitcnt vmcnt(13)
	v_mul_f32_e32 v56, v59, v107
	v_fmac_f32_e32 v56, v58, v105
	v_fmac_f32_e32 v56, v60, v106
	v_fmac_f32_e32 v56, v61, v104
	s_nop 1
	v_add_f32_dpp v56, v56, v56 quad_perm:[1,0,3,2] row_mask:0xf bank_mask:0xf bound_ctrl:1
	s_nop 1
	v_add_f32_dpp v56, v56, v56 quad_perm:[2,3,0,1] row_mask:0xf bank_mask:0xf bound_ctrl:1
	s_nop 1
	v_add_f32_dpp v56, v56, v56 row_ror:4 row_mask:0xf bank_mask:0xf bound_ctrl:1
	s_nop 1
	v_mov_b32_dpp v57, v56 row_ror:8 row_mask:0xf bank_mask:0xf bound_ctrl:1
	s_and_saveexec_b64 s[0:1], s[6:7]
	v_add_f32_e32 v56, v56, v57
	v_add_f32_e32 v56, v108, v56
	ds_write_b32 v96, v56 offset:416
	s_or_b64 exec, exec, s[0:1]
	s_waitcnt vmcnt(12)
	v_mul_f32_e32 v51, v51, v107
	v_fmac_f32_e32 v51, v50, v105
	v_fmac_f32_e32 v51, v52, v106
	v_fmac_f32_e32 v51, v53, v104
	s_nop 1
	v_add_f32_dpp v50, v51, v51 quad_perm:[1,0,3,2] row_mask:0xf bank_mask:0xf bound_ctrl:1
	s_nop 1
	v_add_f32_dpp v50, v50, v50 quad_perm:[2,3,0,1] row_mask:0xf bank_mask:0xf bound_ctrl:1
	s_nop 1
	v_add_f32_dpp v50, v50, v50 row_ror:4 row_mask:0xf bank_mask:0xf bound_ctrl:1
	s_nop 1
	v_mov_b32_dpp v51, v50 row_ror:8 row_mask:0xf bank_mask:0xf bound_ctrl:1
	s_and_saveexec_b64 s[0:1], s[6:7]
	v_add_f32_e32 v50, v50, v51
	v_add_f32_e32 v50, v108, v50
	ds_write_b32 v96, v50 offset:432
	s_or_b64 exec, exec, s[0:1]
	s_waitcnt vmcnt(11)
	v_mul_f32_e32 v47, v47, v107
	v_fmac_f32_e32 v47, v46, v105
	v_fmac_f32_e32 v47, v48, v106
	v_fmac_f32_e32 v47, v49, v104
	s_nop 1
	v_add_f32_dpp v46, v47, v47 quad_perm:[1,0,3,2] row_mask:0xf bank_mask:0xf bound_ctrl:1
	s_nop 1
	v_add_f32_dpp v46, v46, v46 quad_perm:[2,3,0,1] row_mask:0xf bank_mask:0xf bound_ctrl:1
	s_nop 1
	v_add_f32_dpp v46, v46, v46 row_ror:4 row_mask:0xf bank_mask:0xf bound_ctrl:1
	s_nop 1
	v_mov_b32_dpp v47, v46 row_ror:8 row_mask:0xf bank_mask:0xf bound_ctrl:1
	s_and_saveexec_b64 s[0:1], s[6:7]
	v_add_f32_e32 v46, v46, v47
	v_add_f32_e32 v46, v108, v46
	ds_write_b32 v96, v46 offset:448
	s_or_b64 exec, exec, s[0:1]
	s_waitcnt vmcnt(10)
	v_mul_f32_e32 v43, v43, v107
	v_fmac_f32_e32 v43, v42, v105
	v_fmac_f32_e32 v43, v44, v106
	v_fmac_f32_e32 v43, v45, v104
	s_nop 1
	v_add_f32_dpp v42, v43, v43 quad_perm:[1,0,3,2] row_mask:0xf bank_mask:0xf bound_ctrl:1
	s_nop 1
	v_add_f32_dpp v42, v42, v42 quad_perm:[2,3,0,1] row_mask:0xf bank_mask:0xf bound_ctrl:1
	s_nop 1
	v_add_f32_dpp v42, v42, v42 row_ror:4 row_mask:0xf bank_mask:0xf bound_ctrl:1
	s_nop 1
	v_mov_b32_dpp v43, v42 row_ror:8 row_mask:0xf bank_mask:0xf bound_ctrl:1
	s_and_saveexec_b64 s[0:1], s[6:7]
	v_add_f32_e32 v42, v42, v43
	v_add_f32_e32 v42, v108, v42
	ds_write_b32 v96, v42 offset:464
	s_or_b64 exec, exec, s[0:1]
	s_waitcnt vmcnt(9)
	v_mul_f32_e32 v39, v39, v107
	v_fmac_f32_e32 v39, v38, v105
	v_fmac_f32_e32 v39, v40, v106
	v_fmac_f32_e32 v39, v41, v104
	s_nop 1
	v_add_f32_dpp v38, v39, v39 quad_perm:[1,0,3,2] row_mask:0xf bank_mask:0xf bound_ctrl:1
	s_nop 1
	v_add_f32_dpp v38, v38, v38 quad_perm:[2,3,0,1] row_mask:0xf bank_mask:0xf bound_ctrl:1
	s_nop 1
	v_add_f32_dpp v38, v38, v38 row_ror:4 row_mask:0xf bank_mask:0xf bound_ctrl:1
	s_nop 1
	v_mov_b32_dpp v39, v38 row_ror:8 row_mask:0xf bank_mask:0xf bound_ctrl:1
	s_and_saveexec_b64 s[0:1], s[6:7]
	v_add_f32_e32 v38, v38, v39
	v_add_f32_e32 v38, v108, v38
	ds_write_b32 v96, v38 offset:480
	s_or_b64 exec, exec, s[0:1]
	s_waitcnt vmcnt(8)
	v_mul_f32_e32 v35, v35, v107
	v_fmac_f32_e32 v35, v34, v105
	v_fmac_f32_e32 v35, v36, v106
	v_fmac_f32_e32 v35, v37, v104
	s_nop 1
	v_add_f32_dpp v34, v35, v35 quad_perm:[1,0,3,2] row_mask:0xf bank_mask:0xf bound_ctrl:1
	s_nop 1
	v_add_f32_dpp v34, v34, v34 quad_perm:[2,3,0,1] row_mask:0xf bank_mask:0xf bound_ctrl:1
	s_nop 1
	v_add_f32_dpp v34, v34, v34 row_ror:4 row_mask:0xf bank_mask:0xf bound_ctrl:1
	s_nop 1
	v_mov_b32_dpp v35, v34 row_ror:8 row_mask:0xf bank_mask:0xf bound_ctrl:1
	s_and_saveexec_b64 s[0:1], s[6:7]
	v_add_f32_e32 v34, v34, v35
	v_add_f32_e32 v34, v108, v34
	ds_write_b32 v96, v34 offset:496
	s_or_b64 exec, exec, s[0:1]
	s_waitcnt lgkmcnt(0)
	ds_read_b64 v[34:35], v97
	s_waitcnt lgkmcnt(0)
; __device__ __forceinline__ float softplus2_(float z2) { return fmaxf(z2, 0.f) + log1pf(exp2f(-fabsf(z2))) * LOG2E; }
; template <int NB>
; __device__ __forceinline__ void sb_decode_task(const Params& P, float* lds, int task) {
;     ...
;     const float z0 = zl[2 * lane], z1 = zl[2 * lane + 1];
;     const float sp0 = softplus2_(z0), sp1 = softplus2_(z1);
	v_cmp_gt_f32_e64 vcc, |v34|, s49
	s_nop 1
	v_cndmask_b32_e32 v37, 0, v101, vcc
	v_sub_f32_e64 v37, v37, |v34|
	v_exp_f32_e32 v37, v37
	v_max_f32_e32 v36, v34, v34
	v_max_f32_e32 v38, 0, v36
	v_cndmask_b32_e32 v36, 0, v100, vcc
	v_ldexp_f32 v39, v37, v36
	v_add_f32_e32 v40, 1.0, v39
	v_add_f32_e32 v36, -1.0, v40
	v_sub_f32_e32 v37, v36, v40
	v_add_f32_e32 v37, 1.0, v37
	v_sub_f32_e32 v36, v39, v36
	v_add_f32_e32 v41, v36, v37
	v_frexp_mant_f32_e32 v36, v40
	v_cmp_gt_f32_e32 vcc, s50, v36
	v_cvt_f64_f32_e32 v[36:37], v40
	v_frexp_exp_i32_f64_e32 v36, v[36:37]
	v_subbrev_co_u32_e32 v36, vcc, 0, v36, vcc
	v_sub_u32_e32 v37, 0, v36
	v_ldexp_f32 v40, v40, v37
	v_ldexp_f32 v37, v41, v37
	v_add_f32_e32 v41, -1.0, v40
	v_add_f32_e32 v42, 1.0, v41
	v_sub_f32_e32 v42, v40, v42
	v_add_f32_e32 v42, v37, v42
	v_add_f32_e32 v43, v41, v42
	v_sub_f32_e32 v41, v41, v43
	v_add_f32_e32 v41, v42, v41
	v_add_f32_e32 v42, 1.0, v40
	v_add_f32_e32 v44, -1.0, v42
	v_sub_f32_e32 v40, v40, v44
	v_add_f32_e32 v37, v37, v40
	v_add_f32_e32 v40, v42, v37
	v_sub_f32_e32 v42, v42, v40
	v_add_f32_e32 v37, v37, v42
	v_rcp_f32_e32 v42, v40
	v_cvt_f32_i32_e32 v36, v36
	v_cmp_neq_f32_e32 vcc, s52, v39
	v_mul_f32_e32 v44, v43, v42
	v_mul_f32_e32 v45, v40, v44
	v_fma_f32 v46, v44, v40, -v45
	v_fmac_f32_e32 v46, v44, v37
	v_add_f32_e32 v47, v45, v46
	v_sub_f32_e32 v48, v43, v47
	v_sub_f32_e32 v43, v43, v48
	v_sub_f32_e32 v45, v47, v45
	v_sub_f32_e32 v43, v43, v47
	v_add_f32_e32 v41, v41, v43
	v_sub_f32_e32 v43, v45, v46
	v_add_f32_e32 v41, v43, v41
	v_add_f32_e32 v43, v48, v41
	v_mul_f32_e32 v45, v42, v43
	v_mul_f32_e32 v46, v40, v45
	v_fma_f32 v40, v45, v40, -v46
	v_fmac_f32_e32 v40, v45, v37
	v_sub_f32_e32 v37, v48, v43
	v_add_f32_e32 v37, v41, v37
	v_add_f32_e32 v41, v46, v40
	v_sub_f32_e32 v47, v43, v41
	v_sub_f32_e32 v43, v43, v47
	v_sub_f32_e32 v46, v41, v46
	v_sub_f32_e32 v41, v43, v41
	v_add_f32_e32 v37, v37, v41
	v_sub_f32_e32 v40, v46, v40
	v_add_f32_e32 v37, v40, v37
	v_add_f32_e32 v40, v44, v45
	v_add_f32_e32 v37, v47, v37
	v_sub_f32_e32 v41, v40, v44
	v_mul_f32_e32 v37, v42, v37
	v_sub_f32_e32 v41, v45, v41
	v_add_f32_e32 v37, v41, v37
	v_mul_f32_e32 v44, 0x3f317218, v36
	v_add_f32_e32 v41, v40, v37
	v_fma_f32 v45, v36, s51, -v44
	v_mul_f32_e32 v42, v41, v41
	v_fmac_f32_e32 v45, 0xb102e308, v36
	v_sub_f32_e32 v36, v41, v40
	v_fmamk_f32 v43, v42, 0x3e9b6dac, v98
	v_sub_f32_e32 v36, v37, v36
	v_add_f32_e32 v37, v44, v45
	v_fmaak_f32 v43, v42, v43, 0x3f2aaada
	v_sub_f32_e32 v40, v37, v44
	v_ldexp_f32 v44, v41, 1
	v_mul_f32_e32 v41, v41, v42
	v_mul_f32_e32 v41, v41, v43
	v_add_f32_e32 v42, v44, v41
	v_sub_f32_e32 v43, v42, v44
	v_ldexp_f32 v36, v36, 1
	v_sub_f32_e32 v41, v41, v43
	v_add_f32_e32 v36, v36, v41
	v_add_f32_e32 v41, v42, v36
	v_sub_f32_e32 v42, v41, v42
	v_sub_f32_e32 v36, v36, v42
	v_add_f32_e32 v42, v37, v41
	v_sub_f32_e32 v43, v42, v37
	v_sub_f32_e32 v44, v42, v43
	v_sub_f32_e32 v40, v45, v40
	v_sub_f32_e32 v37, v37, v44
	v_sub_f32_e32 v41, v41, v43
	v_add_f32_e32 v37, v41, v37
	v_add_f32_e32 v41, v40, v36
	v_sub_f32_e32 v43, v41, v40
	v_sub_f32_e32 v44, v41, v43
	v_sub_f32_e32 v40, v40, v44
	v_sub_f32_e32 v36, v36, v43
	v_add_f32_e32 v37, v41, v37
	v_add_f32_e32 v36, v36, v40
	v_add_f32_e32 v40, v42, v37
	v_sub_f32_e32 v41, v40, v42
	v_sub_f32_e32 v37, v37, v41
	v_add_f32_e32 v36, v36, v37
	v_add_f32_e32 v36, v40, v36
	v_cndmask_b32_e32 v36, v102, v36, vcc
	v_cmp_lt_f32_e64 vcc, |v39|, s53
	s_nop 1
	v_cndmask_b32_e32 v36, v36, v39, vcc
	v_cmp_gt_f32_e64 vcc, |v35|, s49
	v_fmac_f32_e32 v38, 0x3fb8aa3b, v36
	v_max_f32_e32 v36, v35, v35
	v_cndmask_b32_e32 v37, 0, v101, vcc
	v_sub_f32_e64 v37, v37, |v35|
	v_exp_f32_e32 v37, v37
	v_max_f32_e32 v39, 0, v36
	v_cndmask_b32_e32 v36, 0, v100, vcc
	v_sub_f32_e32 v34, v34, v38
	v_ldexp_f32 v40, v37, v36
	v_add_f32_e32 v41, 1.0, v40
	v_add_f32_e32 v36, -1.0, v41
	v_sub_f32_e32 v37, v36, v41
	v_add_f32_e32 v37, 1.0, v37
	v_sub_f32_e32 v36, v40, v36
	v_add_f32_e32 v42, v36, v37
	v_frexp_mant_f32_e32 v36, v41
	v_cmp_gt_f32_e32 vcc, s50, v36
	v_cvt_f64_f32_e32 v[36:37], v41
	v_frexp_exp_i32_f64_e32 v36, v[36:37]
	v_subbrev_co_u32_e32 v36, vcc, 0, v36, vcc
	v_sub_u32_e32 v37, 0, v36
	v_ldexp_f32 v41, v41, v37
	v_ldexp_f32 v37, v42, v37
	v_add_f32_e32 v42, -1.0, v41
	v_add_f32_e32 v43, 1.0, v42
	v_sub_f32_e32 v43, v41, v43
	v_add_f32_e32 v43, v37, v43
	v_add_f32_e32 v44, v42, v43
	v_sub_f32_e32 v42, v42, v44
	v_add_f32_e32 v42, v43, v42
	v_add_f32_e32 v43, 1.0, v41
	v_add_f32_e32 v45, -1.0, v43
	v_sub_f32_e32 v41, v41, v45
	v_add_f32_e32 v37, v37, v41
	v_add_f32_e32 v41, v43, v37
	v_sub_f32_e32 v43, v43, v41
	v_add_f32_e32 v37, v37, v43
	v_rcp_f32_e32 v43, v41
	v_cvt_f32_i32_e32 v36, v36
	v_cmp_neq_f32_e32 vcc, s52, v40
	v_mul_f32_e32 v45, v44, v43
	v_mul_f32_e32 v46, v41, v45
	v_fma_f32 v47, v45, v41, -v46
	v_fmac_f32_e32 v47, v45, v37
	v_add_f32_e32 v48, v46, v47
	v_sub_f32_e32 v49, v44, v48
	v_sub_f32_e32 v44, v44, v49
	v_sub_f32_e32 v46, v48, v46
	v_sub_f32_e32 v44, v44, v48
	v_add_f32_e32 v42, v42, v44
	v_sub_f32_e32 v44, v46, v47
	v_add_f32_e32 v42, v44, v42
	v_add_f32_e32 v44, v49, v42
	v_mul_f32_e32 v46, v43, v44
	v_mul_f32_e32 v47, v41, v46
	v_fma_f32 v41, v46, v41, -v47
	v_fmac_f32_e32 v41, v46, v37
	v_sub_f32_e32 v37, v49, v44
	v_add_f32_e32 v37, v42, v37
	v_add_f32_e32 v42, v47, v41
	v_sub_f32_e32 v48, v44, v42
	v_sub_f32_e32 v44, v44, v48
	v_sub_f32_e32 v47, v42, v47
	v_sub_f32_e32 v42, v44, v42
	v_add_f32_e32 v37, v37, v42
	v_sub_f32_e32 v41, v47, v41
	v_add_f32_e32 v37, v41, v37
	v_add_f32_e32 v41, v45, v46
	v_add_f32_e32 v37, v48, v37
	v_sub_f32_e32 v42, v41, v45
	v_mul_f32_e32 v37, v43, v37
; __device__ __forceinline__ float softplus2_(float z2) { return fmaxf(z2, 0.f) + log1pf(exp2f(-fabsf(z2))) * LOG2E; }
; template <int NB>
; __device__ __forceinline__ void sb_decode_task(const Params& P, float* lds, int task) {
;     ...
;     const float sp0 = softplus2_(z0), sp1 = softplus2_(z1);
;     float incl = sp0 + sp1;
; #pragma unroll
;     for (int off = 1; off < 64; off <<= 1) { const float t = __shfl_down(incl, off); if (lane + off < 64) incl += t; }
;     const float excl = incl - (sp0 + sp1);
;     wl[2 * lane] = exp2f(z0 - sp0 - (excl + sp1));
;     wl[2 * lane + 1] = exp2f(z1 - sp1 - excl);
;     const float Ltot = __shfl(incl, 0);
;     asm volatile("s_waitcnt lgkmcnt(0)" ::: "memory");
;     __builtin_amdgcn_wave_barrier();
;     float4 o4 = make_float4(0.f, 0.f, 0.f, 0.f);
; #pragma unroll
;     for (int vb = 0; vb < NBT; ++vb) {
;         if (vb + 1 < NBT) {
; #pragma unroll
;             for (int i = 0; i < NB; ++i) nx[i] = *(const float4*)(Vp + (size_t)(4 * NB * (vb + 1) + 4 * i + g) * (SH * HD)); }
; #pragma unroll
;         for (int i = 0; i < NB; ++i) { const float w = wl[4 * NB * vb + 4 * i + g]; o4.x += w * cur[i].x; o4.y += w * cur[i].y; o4.z += w * cur[i].z; o4.w += w * cur[i].w; }
	v_sub_f32_e32 v42, v46, v42
	v_add_f32_e32 v37, v42, v37
	v_mul_f32_e32 v45, 0x3f317218, v36
	v_add_f32_e32 v42, v41, v37
	v_fma_f32 v46, v36, s51, -v45
	v_mul_f32_e32 v43, v42, v42
	v_fmac_f32_e32 v46, 0xb102e308, v36
	v_sub_f32_e32 v36, v42, v41
	v_fmamk_f32 v44, v43, 0x3e9b6dac, v98
	v_sub_f32_e32 v36, v37, v36
	v_add_f32_e32 v37, v45, v46
	v_fmaak_f32 v44, v43, v44, 0x3f2aaada
	v_sub_f32_e32 v41, v37, v45
	v_ldexp_f32 v45, v42, 1
	v_mul_f32_e32 v42, v42, v43
	v_mul_f32_e32 v42, v42, v44
	v_add_f32_e32 v43, v45, v42
	v_sub_f32_e32 v44, v43, v45
	v_ldexp_f32 v36, v36, 1
	v_sub_f32_e32 v42, v42, v44
	v_add_f32_e32 v36, v36, v42
	v_add_f32_e32 v42, v43, v36
	v_sub_f32_e32 v43, v42, v43
	v_sub_f32_e32 v36, v36, v43
	v_add_f32_e32 v43, v37, v42
	v_sub_f32_e32 v44, v43, v37
	v_sub_f32_e32 v45, v43, v44
	v_sub_f32_e32 v41, v46, v41
	v_sub_f32_e32 v37, v37, v45
	v_sub_f32_e32 v42, v42, v44
	v_add_f32_e32 v37, v42, v37
	v_add_f32_e32 v42, v41, v36
	v_sub_f32_e32 v44, v42, v41
	v_sub_f32_e32 v45, v42, v44
	v_sub_f32_e32 v41, v41, v45
	v_sub_f32_e32 v36, v36, v44
	v_add_f32_e32 v37, v42, v37
	v_add_f32_e32 v36, v36, v41
	v_add_f32_e32 v41, v43, v37
	v_sub_f32_e32 v42, v41, v43
	v_sub_f32_e32 v37, v37, v42
	v_add_f32_e32 v36, v36, v37
	v_add_f32_e32 v36, v41, v36
	v_cndmask_b32_e32 v36, v102, v36, vcc
	v_cmp_lt_f32_e64 vcc, |v40|, s53
	v_and_b32_e32 v37, 63, v103
	s_nop 0
	v_cndmask_b32_e32 v36, v36, v40, vcc
	v_cmp_ne_u32_e32 vcc, 63, v37
	v_fmac_f32_e32 v39, 0x3fb8aa3b, v36
	v_add_f32_e32 v36, v38, v39
	v_addc_co_u32_e32 v40, vcc, 0, v103, vcc
	v_lshlrev_b32_e32 v106, 2, v40
	ds_bpermute_b32 v40, v106, v36
	v_cmp_gt_u32_e32 vcc, 62, v37
	v_sub_f32_e32 v35, v35, v39
	s_waitcnt lgkmcnt(0)
	v_add_f32_e32 v40, v36, v40
	v_cndmask_b32_e64 v41, 0, 2, vcc
	v_cndmask_b32_e64 v40, v40, v36, s[8:9]
	v_add_lshl_u32 v107, v41, v103, 2
	ds_bpermute_b32 v41, v107, v40
	v_cmp_gt_u32_e32 vcc, 60, v37
	s_waitcnt lgkmcnt(0)
	v_add_f32_e32 v41, v40, v41
	v_cndmask_b32_e64 v40, v40, v41, s[10:11]
	v_cndmask_b32_e64 v41, 0, 4, vcc
	v_add_lshl_u32 v108, v41, v103, 2
	ds_bpermute_b32 v41, v108, v40
	v_cmp_gt_u32_e32 vcc, 56, v37
	s_waitcnt lgkmcnt(0)
	v_add_f32_e32 v41, v40, v41
	v_cndmask_b32_e64 v40, v40, v41, s[12:13]
	v_cndmask_b32_e64 v41, 0, 8, vcc
	v_add_lshl_u32 v109, v41, v103, 2
	ds_bpermute_b32 v41, v109, v40
	v_cmp_gt_u32_e32 vcc, 48, v37
	s_waitcnt lgkmcnt(0)
	v_add_f32_e32 v41, v40, v41
	v_cndmask_b32_e64 v37, 0, 16, vcc
	v_cndmask_b32_e64 v40, v40, v41, s[14:15]
	v_add_lshl_u32 v110, v37, v103, 2
	ds_bpermute_b32 v37, v110, v40
	s_waitcnt lgkmcnt(0)
	v_add_f32_e32 v37, v40, v37
	v_cndmask_b32_e64 v37, v40, v37, s[16:17]
	v_lshlrev_b32_e32 v40, 2, v103
	v_or_b32_e32 v111, 0x80, v40
	ds_bpermute_b32 v41, v111, v37
	v_and_b32_e32 v104, 0x100, v40
	s_waitcnt lgkmcnt(0)
	v_add_f32_e32 v41, v37, v41
	v_cndmask_b32_e64 v44, v37, v41, s[18:19]
	v_sub_f32_e32 v36, v44, v36
	v_add_f32_e32 v37, v39, v36
	v_sub_f32_e32 v34, v34, v37
	v_cmp_gt_f32_e32 vcc, s54, v34
	v_sub_f32_e32 v35, v35, v36
	s_nop 0
	v_cndmask_b32_e32 v37, 0, v101, vcc
	v_add_f32_e32 v34, v34, v37
	v_cndmask_b32_e32 v37, 0, v100, vcc
	v_cmp_gt_f32_e32 vcc, s54, v35
	v_exp_f32_e32 v34, v34
	s_nop 0
	v_cndmask_b32_e32 v36, 0, v101, vcc
	v_add_f32_e32 v35, v35, v36
	v_exp_f32_e32 v35, v35
	v_cndmask_b32_e32 v36, 0, v100, vcc
	v_ldexp_f32 v34, v34, v37
	v_ldexp_f32 v35, v35, v36
	ds_write_b64 v97, v[34:35] offset:512
	s_waitcnt lgkmcnt(0)
	ds_read2_b32 v[34:35], v96 offset0:128 offset1:132
	ds_read2_b32 v[42:43], v96 offset0:136 offset1:140
	ds_read2_b32 v[66:67], v96 offset0:144 offset1:148
	ds_read2_b32 v[68:69], v96 offset0:152 offset1:156
	ds_read2_b32 v[74:75], v96 offset0:160 offset1:164
	ds_read2_b32 v[76:77], v96 offset0:168 offset1:172
	ds_read2_b32 v[38:39], v96 offset0:176 offset1:180
	ds_read2_b32 v[40:41], v96 offset0:184 offset1:188
	s_waitcnt vmcnt(7) lgkmcnt(7)
	v_pk_fma_f32 v[70:71], v[30:31], v[34:35], 0 op_sel_hi:[1,0,0]
	v_add_co_u32_e32 v30, vcc, s55, v54
	v_pk_fma_f32 v[72:73], v[32:33], v[34:35], 0 op_sel_hi:[1,0,0]
	s_nop 0
	v_addc_co_u32_e32 v31, vcc, 0, v55, vcc
	v_add_co_u32_e32 v34, vcc, s83, v54
	v_mov_b32_e32 v64, v35
	s_nop 0
	v_addc_co_u32_e32 v35, vcc, 0, v55, vcc
	v_add_co_u32_e32 v46, vcc, s86, v54
	s_waitcnt vmcnt(6)
	v_pk_fma_f32 v[2:3], v[2:3], v[64:65], v[70:71] op_sel_hi:[1,0,1]
	v_addc_co_u32_e32 v47, vcc, 0, v55, vcc
	v_add_co_u32_e32 v50, vcc, s87, v54
	global_load_dwordx4 v[46:49], v[46:47], off nt
	s_nop 0
	v_addc_co_u32_e32 v51, vcc, 0, v55, vcc
	v_add_co_u32_e32 v56, vcc, s88, v54
	global_load_dwordx4 v[50:53], v[50:51], off offset:2048 nt
	s_nop 0
	v_addc_co_u32_e32 v57, vcc, 0, v55, vcc
	v_add_co_u32_e32 v60, vcc, s89, v54
	global_load_dwordx4 v[56:59], v[56:57], off nt
	s_nop 0
	v_addc_co_u32_e32 v61, vcc, 0, v55, vcc
	global_load_dwordx4 v[60:63], v[60:61], off offset:2048 nt
	s_waitcnt lgkmcnt(6)
	v_mov_b32_e32 v78, v43
	s_waitcnt vmcnt(9)
	v_pk_fma_f32 v[2:3], v[6:7], v[42:43], v[2:3] op_sel_hi:[1,0,1]
	s_waitcnt lgkmcnt(5)
	v_mov_b32_e32 v80, v67
	s_waitcnt vmcnt(7)
	v_pk_fma_f32 v[2:3], v[14:15], v[78:79], v[2:3] op_sel_hi:[1,0,1]
	s_waitcnt lgkmcnt(4)
	v_mov_b32_e32 v92, v69
	v_pk_fma_f32 v[2:3], v[10:11], v[66:67], v[2:3] op_sel_hi:[1,0,1]
	s_waitcnt lgkmcnt(3)
	v_mov_b32_e32 v10, v75
	s_waitcnt vmcnt(6)
	v_pk_fma_f32 v[2:3], v[18:19], v[80:81], v[2:3] op_sel_hi:[1,0,1]
	s_waitcnt lgkmcnt(2)
	v_mov_b32_e32 v14, v77
	s_waitcnt vmcnt(5)
	v_pk_fma_f32 v[2:3], v[22:23], v[68:69], v[2:3] op_sel_hi:[1,0,1]
	global_load_dwordx4 v[30:33], v[30:31], off nt
	s_waitcnt vmcnt(5)
; template <int NB>
; __device__ __forceinline__ void sb_decode_task(const Params& P, float* lds, int task) {
;     ...
; #pragma unroll
;     for (int vb = 0; vb < NBT; ++vb) {
;         if (vb + 1 < NBT) {
; #pragma unroll
;             for (int i = 0; i < NB; ++i) nx[i] = *(const float4*)(Vp + (size_t)(4 * NB * (vb + 1) + 4 * i + g) * (SH * HD)); }
; #pragma unroll
;         for (int i = 0; i < NB; ++i) { const float w = wl[4 * NB * vb + 4 * i + g]; o4.x += w * cur[i].x; o4.y += w * cur[i].y; o4.z += w * cur[i].z; o4.w += w * cur[i].w; }
; #pragma unroll
;         for (int i = 0; i < NB; ++i) cur[i] = nx[i];
	v_pk_fma_f32 v[2:3], v[26:27], v[92:93], v[2:3] op_sel_hi:[1,0,1]
	global_load_dwordx4 v[34:37], v[34:35], off offset:2048 nt
	s_waitcnt vmcnt(5)
	v_pk_fma_f32 v[2:3], v[46:47], v[74:75], v[2:3] op_sel_hi:[1,0,1]
	s_waitcnt vmcnt(4)
	v_pk_fma_f32 v[2:3], v[50:51], v[10:11], v[2:3] op_sel_hi:[1,0,1]
	s_waitcnt vmcnt(3)
	v_pk_fma_f32 v[2:3], v[56:57], v[76:77], v[2:3] op_sel_hi:[1,0,1]
	s_waitcnt vmcnt(2)
	v_pk_fma_f32 v[6:7], v[60:61], v[14:15], v[2:3] op_sel_hi:[1,0,1]
	v_pk_fma_f32 v[2:3], v[4:5], v[64:65], v[72:73] op_sel_hi:[1,0,1]
	v_add_co_u32_e32 v4, vcc, s90, v54
	v_pk_fma_f32 v[2:3], v[8:9], v[42:43], v[2:3] op_sel_hi:[1,0,1]
	s_nop 0
	v_addc_co_u32_e32 v5, vcc, 0, v55, vcc
	v_pk_fma_f32 v[2:3], v[16:17], v[78:79], v[2:3] op_sel_hi:[1,0,1]
	s_waitcnt lgkmcnt(0)
	v_mov_b32_e32 v42, v41
	v_pk_fma_f32 v[2:3], v[12:13], v[66:67], v[2:3] op_sel_hi:[1,0,1]
	s_waitcnt vmcnt(1)
	v_pk_fma_f32 v[6:7], v[30:31], v[38:39], v[6:7] op_sel_hi:[1,0,1]
	v_pk_fma_f32 v[2:3], v[20:21], v[80:81], v[2:3] op_sel_hi:[1,0,1]
	s_nop 0
	v_pk_fma_f32 v[2:3], v[24:25], v[68:69], v[2:3] op_sel_hi:[1,0,1]
	s_nop 0
	v_pk_fma_f32 v[2:3], v[28:29], v[92:93], v[2:3] op_sel_hi:[1,0,1]
	v_mov_b32_e32 v28, v39
	v_pk_fma_f32 v[2:3], v[48:49], v[74:75], v[2:3] op_sel_hi:[1,0,1]
	s_waitcnt vmcnt(0)
	v_pk_fma_f32 v[6:7], v[34:35], v[28:29], v[6:7] op_sel_hi:[1,0,1]
	v_pk_fma_f32 v[2:3], v[52:53], v[10:11], v[2:3] op_sel_hi:[1,0,1]
	s_nop 0
	v_pk_fma_f32 v[2:3], v[58:59], v[76:77], v[2:3] op_sel_hi:[1,0,1]
	s_nop 0
	v_pk_fma_f32 v[2:3], v[62:63], v[14:15], v[2:3] op_sel_hi:[1,0,1]
	ds_read2_b32 v[14:15], v96 offset0:192 offset1:196
	ds_read2_b32 v[12:13], v96 offset0:200 offset1:204
	ds_read2_b32 v[10:11], v96 offset0:208 offset1:212
	ds_read2_b32 v[8:9], v96 offset0:216 offset1:220
	global_load_dwordx4 v[16:19], v[4:5], off nt
	v_add_co_u32_e32 v4, vcc, s91, v54
	v_pk_fma_f32 v[2:3], v[32:33], v[38:39], v[2:3] op_sel_hi:[1,0,1]
	s_nop 0
	v_addc_co_u32_e32 v5, vcc, 0, v55, vcc
	global_load_dwordx4 v[20:23], v[4:5], off offset:2048 nt
	v_add_co_u32_e32 v4, vcc, s92, v54
	v_pk_fma_f32 v[2:3], v[36:37], v[28:29], v[2:3] op_sel_hi:[1,0,1]
	s_nop 0
	v_addc_co_u32_e32 v5, vcc, 0, v55, vcc
	global_load_dwordx4 v[24:27], v[4:5], off nt
	v_add_co_u32_e32 v4, vcc, s93, v54
	s_waitcnt lgkmcnt(0)
	v_mov_b32_e32 v36, v9
	v_addc_co_u32_e32 v5, vcc, 0, v55, vcc
	global_load_dwordx4 v[46:49], v[4:5], off offset:2048 nt
	v_add_co_u32_e32 v4, vcc, s94, v54
	ds_read2_b32 v[30:31], v96 offset0:224 offset1:228
	s_nop 0
	v_addc_co_u32_e32 v5, vcc, 0, v55, vcc
	global_load_dwordx4 v[50:53], v[4:5], off nt
	v_add_co_u32_e32 v4, vcc, s95, v54
	s_waitcnt vmcnt(4)
	v_pk_fma_f32 v[2:3], v[18:19], v[40:41], v[2:3] op_sel_hi:[1,0,1]
	v_addc_co_u32_e32 v5, vcc, 0, v55, vcc
	global_load_dwordx4 v[56:59], v[4:5], off offset:2048 nt
	v_add_co_u32_e32 v4, vcc, s96, v54
	s_waitcnt vmcnt(4)
	v_pk_fma_f32 v[2:3], v[22:23], v[42:43], v[2:3] op_sel_hi:[1,0,1]
	v_addc_co_u32_e32 v5, vcc, 0, v55, vcc
	global_load_dwordx4 v[60:63], v[4:5], off nt
	v_add_co_u32_e32 v4, vcc, s97, v54
	s_waitcnt vmcnt(4)
	v_pk_fma_f32 v[2:3], v[26:27], v[14:15], v[2:3] op_sel_hi:[1,0,1]
	v_addc_co_u32_e32 v5, vcc, 0, v55, vcc
	global_load_dwordx4 v[64:67], v[4:5], off offset:2048 nt
	v_add_co_u32_e32 v4, vcc, s22, v54
	v_mov_b32_e32 v18, v15
	s_nop 0
	v_addc_co_u32_e32 v5, vcc, 0, v55, vcc
	global_load_dwordx4 v[68:71], v[4:5], off nt
	v_pk_fma_f32 v[6:7], v[16:17], v[40:41], v[6:7] op_sel_hi:[1,0,1]
	s_waitcnt vmcnt(5)
	v_pk_fma_f32 v[2:3], v[48:49], v[18:19], v[2:3] op_sel_hi:[1,0,1]
	v_pk_fma_f32 v[6:7], v[20:21], v[42:43], v[6:7] op_sel_hi:[1,0,1]
	s_waitcnt vmcnt(4)
	v_pk_fma_f32 v[2:3], v[52:53], v[12:13], v[2:3] op_sel_hi:[1,0,1]
	v_mov_b32_e32 v22, v13
	v_pk_fma_f32 v[6:7], v[24:25], v[14:15], v[6:7] op_sel_hi:[1,0,1]
	v_mov_b32_e32 v26, v11
	v_pk_fma_f32 v[6:7], v[46:47], v[18:19], v[6:7] op_sel_hi:[1,0,1]
	s_waitcnt vmcnt(3)
	v_pk_fma_f32 v[2:3], v[58:59], v[22:23], v[2:3] op_sel_hi:[1,0,1]
	v_pk_fma_f32 v[6:7], v[50:51], v[12:13], v[6:7] op_sel_hi:[1,0,1]
	s_waitcnt vmcnt(2)
	v_pk_fma_f32 v[2:3], v[62:63], v[10:11], v[2:3] op_sel_hi:[1,0,1]
	v_pk_fma_f32 v[6:7], v[56:57], v[22:23], v[6:7] op_sel_hi:[1,0,1]
	s_waitcnt vmcnt(1)
; template <int NB>
; __device__ __forceinline__ void sb_decode_task(const Params& P, float* lds, int task) {
;     ...
; #pragma unroll
;     for (int vb = 0; vb < NBT; ++vb) {
;         if (vb + 1 < NBT) {
; #pragma unroll
;             for (int i = 0; i < NB; ++i) nx[i] = *(const float4*)(Vp + (size_t)(4 * NB * (vb + 1) + 4 * i + g) * (SH * HD)); }
; #pragma unroll
;         for (int i = 0; i < NB; ++i) { const float w = wl[4 * NB * vb + 4 * i + g]; o4.x += w * cur[i].x; o4.y += w * cur[i].y; o4.z += w * cur[i].z; o4.w += w * cur[i].w; }
; #pragma unroll
;         for (int i = 0; i < NB; ++i) cur[i] = nx[i];
;     }
; #pragma unroll
;     for (int off = 16; off < 64; off <<= 1) { o4.x += __shfl_xor(o4.x, off); o4.y += __shfl_xor(o4.y, off); o4.z += __shfl_xor(o4.z, off); o4.w += __shfl_xor(o4.w, off); }
;     if (g == 0) *(float4*)(dpart + (size_t)task * HD + 4 * c) = o4;
;     if (lane == 0) dl[task] = Ltot;
;     __builtin_amdgcn_wave_barrier();
	v_pk_fma_f32 v[2:3], v[66:67], v[26:27], v[2:3] op_sel_hi:[1,0,1]
	v_pk_fma_f32 v[6:7], v[60:61], v[10:11], v[6:7] op_sel_hi:[1,0,1]
	v_and_b32_e32 v10, 64, v103
	v_pk_fma_f32 v[6:7], v[64:65], v[26:27], v[6:7] op_sel_hi:[1,0,1]
	v_add_u32_e32 v37, 64, v10
	v_xor_b32_e32 v10, 16, v103
	s_waitcnt vmcnt(0)
	v_pk_fma_f32 v[32:33], v[70:71], v[8:9], v[2:3] op_sel_hi:[1,0,1]
	v_add_co_u32_e32 v2, vcc, s23, v54
	v_pk_fma_f32 v[34:35], v[68:69], v[8:9], v[6:7] op_sel_hi:[1,0,1]
	s_nop 0
	v_addc_co_u32_e32 v3, vcc, 0, v55, vcc
	v_add_co_u32_e32 v6, vcc, s24, v54
	global_load_dwordx4 v[2:5], v[2:3], off offset:2048 nt
	s_nop 0
	v_addc_co_u32_e32 v7, vcc, 0, v55, vcc
	v_cmp_lt_i32_e32 vcc, v10, v37
	global_load_dwordx4 v[6:9], v[6:7], off nt
	ds_read2_b32 v[42:43], v96 offset0:232 offset1:236
	ds_read2_b32 v[40:41], v96 offset0:240 offset1:244
	ds_read2_b32 v[38:39], v96 offset0:248 offset1:252
	v_cndmask_b32_e32 v10, v103, v10, vcc
	v_lshlrev_b32_e32 v105, 2, v10
	v_add_co_u32_e32 v10, vcc, s72, v54
	s_waitcnt lgkmcnt(1)
	v_mov_b32_e32 v56, v41
	v_addc_co_u32_e32 v11, vcc, 0, v55, vcc
	v_add_co_u32_e32 v14, vcc, s73, v54
	global_load_dwordx4 v[10:13], v[10:11], off offset:2048 nt
	s_nop 0
	v_addc_co_u32_e32 v15, vcc, 0, v55, vcc
	v_add_co_u32_e32 v18, vcc, s74, v54
	global_load_dwordx4 v[14:17], v[14:15], off nt
	s_nop 0
	v_addc_co_u32_e32 v19, vcc, 0, v55, vcc
	v_add_co_u32_e32 v22, vcc, s75, v54
	global_load_dwordx4 v[18:21], v[18:19], off offset:2048 nt
	s_nop 0
	v_addc_co_u32_e32 v23, vcc, 0, v55, vcc
	v_add_co_u32_e32 v26, vcc, s80, v54
	global_load_dwordx4 v[22:25], v[22:23], off nt
	s_nop 0
	v_addc_co_u32_e32 v27, vcc, 0, v55, vcc
	v_add_co_u32_e32 v46, vcc, s81, v54
	global_load_dwordx4 v[26:29], v[26:27], off offset:2048 nt
	s_nop 0
	v_addc_co_u32_e32 v47, vcc, 0, v55, vcc
	v_add_co_u32_e32 v50, vcc, s82, v54
	global_load_dwordx4 v[46:49], v[46:47], off nt
	s_nop 0
	v_addc_co_u32_e32 v51, vcc, 0, v55, vcc
	global_load_dwordx4 v[50:53], v[50:51], off offset:2048 nt
	v_mov_b32_e32 v54, v43
	s_waitcnt lgkmcnt(0)
	v_mov_b32_e32 v58, v39
	s_waitcnt vmcnt(8)
	v_pk_fma_f32 v[2:3], v[2:3], v[36:37], v[34:35] op_sel_hi:[1,0,1]
	v_mov_b32_e32 v34, v31
	v_pk_fma_f32 v[4:5], v[4:5], v[36:37], v[32:33] op_sel_hi:[1,0,1]
	s_waitcnt vmcnt(7)
	v_pk_fma_f32 v[2:3], v[6:7], v[30:31], v[2:3] op_sel_hi:[1,0,1]
	v_pk_fma_f32 v[4:5], v[8:9], v[30:31], v[4:5] op_sel_hi:[1,0,1]
	s_waitcnt vmcnt(6)
	v_pk_fma_f32 v[2:3], v[10:11], v[34:35], v[2:3] op_sel_hi:[1,0,1]
	v_pk_fma_f32 v[4:5], v[12:13], v[34:35], v[4:5] op_sel_hi:[1,0,1]
	ds_bpermute_b32 v10, v104, v44
	s_waitcnt vmcnt(5)
	v_pk_fma_f32 v[2:3], v[14:15], v[42:43], v[2:3] op_sel_hi:[1,0,1]
	v_pk_fma_f32 v[4:5], v[16:17], v[42:43], v[4:5] op_sel_hi:[1,0,1]
	s_waitcnt vmcnt(4)
	v_pk_fma_f32 v[2:3], v[18:19], v[54:55], v[2:3] op_sel_hi:[1,0,1]
	v_pk_fma_f32 v[4:5], v[20:21], v[54:55], v[4:5] op_sel_hi:[1,0,1]
	s_waitcnt vmcnt(3)
	v_pk_fma_f32 v[2:3], v[22:23], v[40:41], v[2:3] op_sel_hi:[1,0,1]
	v_pk_fma_f32 v[4:5], v[24:25], v[40:41], v[4:5] op_sel_hi:[1,0,1]
	s_waitcnt vmcnt(2)
	v_pk_fma_f32 v[2:3], v[26:27], v[56:57], v[2:3] op_sel_hi:[1,0,1]
	v_pk_fma_f32 v[4:5], v[28:29], v[56:57], v[4:5] op_sel_hi:[1,0,1]
	s_waitcnt vmcnt(1)
	v_pk_fma_f32 v[2:3], v[46:47], v[38:39], v[2:3] op_sel_hi:[1,0,1]
	v_pk_fma_f32 v[4:5], v[48:49], v[38:39], v[4:5] op_sel_hi:[1,0,1]
	s_waitcnt vmcnt(0)
	v_pk_fma_f32 v[2:3], v[50:51], v[58:59], v[2:3] op_sel_hi:[1,0,1]
	ds_bpermute_b32 v6, v105, v2
	ds_bpermute_b32 v7, v105, v3
	v_pk_fma_f32 v[4:5], v[52:53], v[58:59], v[4:5] op_sel_hi:[1,0,1]
	s_waitcnt lgkmcnt(0)
	v_pk_add_f32 v[2:3], v[2:3], v[6:7]
	ds_bpermute_b32 v6, v105, v4
	ds_bpermute_b32 v7, v105, v5
	s_waitcnt lgkmcnt(0)
	v_pk_add_f32 v[4:5], v[4:5], v[6:7]
	v_xor_b32_e32 v6, 32, v103
	v_cmp_lt_i32_e32 vcc, v6, v37
	s_nop 1
	v_cndmask_b32_e32 v6, v103, v6, vcc
	v_lshlrev_b32_e32 v112, 2, v6
	ds_bpermute_b32 v6, v112, v2
	ds_bpermute_b32 v7, v112, v3
	ds_bpermute_b32 v8, v112, v4
	ds_bpermute_b32 v9, v112, v5
	s_and_saveexec_b64 s[0:1], s[20:21]
	s_cbranch_execz .LBB0_1022
	s_ashr_i32 s35, s34, 31
	s_lshl_b64 s[2:3], s[34:35], 8
	v_lshl_add_u64 v[12:13], v[88:89], 0, s[2:3]
	s_waitcnt lgkmcnt(2)
	v_pk_add_f32 v[2:3], v[2:3], v[6:7]
	s_waitcnt lgkmcnt(0)
	v_pk_add_f32 v[4:5], v[4:5], v[8:9]
	global_store_dwordx4 v[12:13], v[2:5], off

; __device__ __forceinline__ void sb_decode_wave_loop(const Params& P, float* lds) {
;     ...
;     for (;;) {
;         const int t = __builtin_amdgcn_readfirstlane((int)nxt);
;         if (t >= DEC_NTASK) break;
;         if (lane == 0) nxt = atomicAdd(qd, 2u);
;         bool thin = false;
;         bool scan_running = false;
;         if (SC_THIN && blockIdx.x < 96) { constexpr unsigned NCHU = SEQ / 16; scan_running = scw[1] < NCHU || scw[2] < NCHU || scw[3] < NCHU || scw[4] < NCHU; thin = scan_running; }
;         thin = true;
;         if (blockIdx.x < 96 && scan_running) { sb_decode_task<4>(P, lds, t); sb_decode_task<4>(P, lds, t + 1); }
.LBB0_1269:
	v_readfirstlane_b32 s34, v98
	s_cmpk_gt_i32 s34, 0x5fff
	s_mov_b64 s[0:1], -1
	s_cbranch_scc1 .LBB0_1268
	s_and_saveexec_b64 s[0:1], s[4:5]
	s_cbranch_execz .LBB0_1274
	s_mov_b64 s[36:37], exec
	v_mbcnt_lo_u32_b32 v2, s36, 0
	v_mbcnt_hi_u32_b32 v2, s37, v2
	v_cmp_eq_u32_e32 vcc, 0, v2
	s_and_saveexec_b64 s[2:3], vcc
	s_cbranch_execz .LBB0_1273
	s_bcnt1_i32_b64 s33, s[36:37]
	s_lshl_b32 s33, s33, 1
	v_readlane_b32 s30, v252, 62
	v_mov_b32_e32 v3, s33
	v_readlane_b32 s31, v252, 63
	s_nop 4
	global_atomic_add v254, v83, v3, s[30:31] sc0
.LBB0_1273:
	s_or_b64 exec, exec, s[2:3]
.LBB0_1274:
	s_or_b64 exec, exec, s[0:1]
	s_and_b64 vcc, exec, s[22:23]
	s_branch .LBB0_1279
	v_mov_b32_e32 v2, s42
	ds_read_b32 v2, v2
	s_movk_i32 s3, 0xff
	s_movk_i32 s2, 0x100
	s_waitcnt lgkmcnt(0)
	v_cmp_lt_u32_e32 vcc, s3, v2
	v_cmp_gt_u32_e64 s[0:1], s2, v2
	s_cbranch_vccz .LBB0_1280
	v_readlane_b32 s0, v252, 60
	s_nop 1
	v_mov_b32_e32 v2, s0
	ds_read_b32 v2, v2
	s_waitcnt lgkmcnt(0)
	v_cmp_lt_u32_e32 vcc, s3, v2
	v_cmp_gt_u32_e64 s[0:1], s2, v2
	s_cbranch_vccz .LBB0_1280
	v_readlane_b32 s0, v252, 58
	s_nop 1
	v_mov_b32_e32 v2, s0
	ds_read_b32 v2, v2
	s_waitcnt lgkmcnt(0)
	v_cmp_lt_u32_e32 vcc, s3, v2
	v_cmp_gt_u32_e64 s[0:1], s2, v2
	s_cbranch_vccz .LBB0_1280
	v_mov_b32_e32 v2, s94
	ds_read_b32 v2, v2
	s_mov_b64 s[0:1], -1
	s_waitcnt lgkmcnt(0)
	v_cmp_lt_u32_e64 s[2:3], s3, v2
	s_and_b64 vcc, exec, s[2:3]
	s_mul_hi_i32 s2, s34, 0x2aaaaaab
	s_cbranch_vccnz .LBB0_1281
	s_branch .LBB0_1418

; __device__ __forceinline__ float bf2f(bf16_t b) { return __uint_as_float(((unsigned)b) << 16); }
; template <int NB>
; __device__ __forceinline__ void sb_decode_task(const Params& P, float* lds, int task) {
;     const int tid = threadIdx.x, lane = tid & 63, wave = tid >> 6;
;     const bf16_t* qb = (const bf16_t*)(P.ws + WS_QB);
;     float* dpart = (float*)(P.ws + WS_DPART); float* dl = (float*)(P.ws + WS_DL);
;     float* zl = lds + DEC_LDS_OFF / 4 + wave * 256; float* wl = zl + 128;
;     const int c = lane & 15, g = lane >> 4;
;     constexpr int NBT = 32 / NB;
;     const int h = task % SH, bj = task / SH, b = bj / NPAGES;
;     const int page = P.page_table[bj];
;     const float* Kp = P.cache_k + ((size_t)page * PAGE * SH + h) * HD + 4 * c;
;     const float* Vp = P.cache_v + ((size_t)page * PAGE * SH + h) * HD + 4 * c;
;     const bf16_t* qp = qb + (size_t)(NTOK + b) * SBW + h * 64 + 4 * c;
;     const float q0 = bf2f(qp[0]), q1 = bf2f(qp[1]), q2 = bf2f(qp[2]), q3 = bf2f(qp[3]);
;     const float bias = P.sb_bias[h] * LOG2E;
;     float4 cur[NB], nx[NB];
; #pragma unroll
;     for (int i = 0; i < NB; ++i) cur[i] = *(const float4*)(Kp + (size_t)(4 * i + g) * (SH * HD));
; #pragma unroll
;     for (int kb = 0; kb < NBT; ++kb) {
;         const float* np = (kb + 1 < NBT) ? Kp + (size_t)(4 * NB * (kb + 1)) * (SH * HD) : Vp;
; #pragma unroll
;         for (int i = 0; i < NB; ++i) nx[i] = *(const float4*)(np + (size_t)(4 * i + g) * (SH * HD));
; #pragma unroll
;         for (int i = 0; i < NB; ++i) { const int s = 4 * NB * kb + 4 * i + g;
;             float part = q0 * cur[i].x + q1 * cur[i].y + q2 * cur[i].z + q3 * cur[i].w; part = sum16(part);
;             if (c == 0) zl[s] = part + bias; }
; __device__ __forceinline__ void sb_decode_wave_loop(const Params& P, float* lds) {
;     ...
;     for (;;) {
;         const int t = __builtin_amdgcn_readfirstlane((int)nxt);
;         if (t >= DEC_NTASK) break;
;         if (lane == 0) nxt = atomicAdd(qd, 2u);
.LBB0_1281:
	v_readlane_b32 s90, v252, 48
	s_lshr_b32 s1, s2, 31
	v_readlane_b32 s91, v252, 49
	s_add_i32 s0, s2, s1
	s_load_dwordx16 s[52:67], s[90:91], 0x0
	s_mul_i32 s3, s0, 6
	s_sub_i32 s36, s34, s3
	s_ashr_i32 s3, s2, 7
	s_add_i32 s3, s3, s1
	s_ashr_i32 s1, s0, 31
	s_lshl_b64 s[0:1], s[0:1], 2
	s_waitcnt lgkmcnt(0)
	s_add_u32 s0, s62, s0
	s_addc_u32 s1, s63, s1
	global_load_dword v2, v83, s[0:1]
	s_add_i32 s0, s3, 0x4000
	s_ashr_i32 s37, s36, 31
	s_mul_hi_i32 s1, s0, 0x300
	s_mulk_i32 s0, 0x300
	s_add_u32 s3, s38, s0
	s_addc_u32 s33, s39, s1
	s_lshl_b32 s0, s36, 6
	s_ashr_i32 s1, s0, 31
	s_lshl_b64 s[0:1], s[0:1], 1
	s_add_u32 s0, s3, s0
	s_addc_u32 s1, s33, s1
	v_readlane_b32 s52, v252, 16
	v_readlane_b32 s53, v252, 17
	v_readlane_b32 s60, v252, 24
	v_readlane_b32 s61, v252, 25
	s_mov_b64 s[52:53], s[60:61]
	v_mov_b32_e32 v93, v83
	v_readlane_b32 s54, v252, 18
	v_readlane_b32 s55, v252, 19
	v_readlane_b32 s56, v252, 20
	v_readlane_b32 s57, v252, 21
	v_readlane_b32 s58, v252, 22
	v_readlane_b32 s59, v252, 23
	v_readlane_b32 s62, v252, 26
	v_readlane_b32 s63, v252, 27
	v_readlane_b32 s64, v252, 28
	v_readlane_b32 s65, v252, 29
	v_readlane_b32 s66, v252, 30
	v_readlane_b32 s67, v252, 31
	s_waitcnt vmcnt(0)
	v_readfirstlane_b32 s101, v254
	v_mov_b32_e32 v253, v2
	s_nop 0
	v_mov_b32_e32 v98, s101
	v_mul_hi_i32 v3, v2, s48
	v_mul_lo_u32 v2, v2, s48
	v_lshl_add_u64 v[94:95], v[2:3], 0, s[36:37]
	v_lshlrev_b64 v[2:3], 8, v[94:95]
	v_lshl_add_u64 v[70:71], v[84:85], 0, v[2:3]
	global_load_dwordx2 v[2:3], v101, s[0:1]
	s_lshl_b64 s[0:1], s[36:37], 2
	s_add_u32 s0, s52, s0
	s_addc_u32 s1, s53, s1
	global_load_dword v22, v83, s[0:1]
	v_lshl_add_u64 v[14:15], v[70:71], 0, v[82:83]
	v_lshl_add_u64 v[16:17], v[70:71], 0, v[92:93]
	global_load_dwordx4 v[18:21], v[14:15], off nt
	s_mov_b64 s[0:1], 0xc000
	global_load_dwordx4 v[62:65], v[16:17], off nt
	s_waitcnt vmcnt(3)
	v_lshlrev_b32_e32 v107, 16, v2
	v_and_b32_e32 v109, 0xffff0000, v2
	v_add_co_u32_e32 v2, vcc, s50, v14
	v_lshlrev_b32_e32 v108, 16, v3
	v_and_b32_e32 v106, 0xffff0000, v3
	v_addc_co_u32_e32 v3, vcc, 0, v15, vcc
	global_load_dwordx4 v[10:13], v[2:3], off offset:2048 nt
	v_add_co_u32_e32 v2, vcc, s51, v14
	s_waitcnt vmcnt(3)
	v_mul_f32_e32 v110, 0x3fb8aa3b, v22
	v_addc_co_u32_e32 v3, vcc, 0, v15, vcc
	global_load_dwordx4 v[6:9], v[2:3], off nt
	v_add_co_u32_e32 v2, vcc, s49, v14
	v_lshl_add_u64 v[22:23], v[70:71], 0, s[0:1]
	s_nop 0
	v_addc_co_u32_e32 v3, vcc, 0, v15, vcc
	v_add_co_u32_e32 v16, vcc, s92, v14
	v_lshl_add_u64 v[30:31], v[22:23], 0, v[82:83]
	s_nop 0
	v_addc_co_u32_e32 v17, vcc, 0, v15, vcc
	global_load_dwordx4 v[58:61], v[16:17], off offset:2048 nt
	v_add_co_u32_e32 v16, vcc, s93, v14
	v_lshl_add_u64 v[22:23], v[22:23], 0, v[92:93]
	s_nop 0
	v_addc_co_u32_e32 v17, vcc, 0, v15, vcc
	v_add_co_u32_e32 v14, vcc, s96, v14
	global_load_dwordx4 v[54:57], v[16:17], off nt
	s_nop 0
	v_addc_co_u32_e32 v15, vcc, 0, v15, vcc
	global_load_dwordx4 v[50:53], v[14:15], off offset:2048 nt
	v_add_co_u32_e32 v14, vcc, s50, v30
	global_load_dwordx4 v[22:25], v[22:23], off nt
	s_nop 0
	v_addc_co_u32_e32 v15, vcc, 0, v31, vcc
	global_load_dwordx4 v[34:37], v[14:15], off offset:2048 nt
	v_add_co_u32_e32 v14, vcc, s51, v30
	global_load_dwordx4 v[2:5], v[2:3], off offset:2048 nt
	s_nop 0
	v_addc_co_u32_e32 v15, vcc, 0, v31, vcc
	global_load_dwordx4 v[26:29], v[14:15], off nt
	v_add_co_u32_e32 v14, vcc, s49, v30
	global_load_dwordx4 v[46:49], v[30:31], off nt
	s_nop 0
	v_addc_co_u32_e32 v15, vcc, 0, v31, vcc
	v_add_co_u32_e32 v32, vcc, s92, v30
	global_load_dwordx4 v[14:17], v[14:15], off offset:2048 nt
	s_nop 0
	v_addc_co_u32_e32 v33, vcc, 0, v31, vcc
	global_load_dwordx4 v[38:41], v[32:33], off offset:2048 nt
	v_add_co_u32_e32 v32, vcc, s93, v30
	s_waitcnt vmcnt(13)
	v_mul_f32_e32 v19, v19, v109
	v_addc_co_u32_e32 v33, vcc, 0, v31, vcc
	v_add_co_u32_e32 v30, vcc, s96, v30
	global_load_dwordx4 v[42:45], v[32:33], off nt
	s_nop 0
	v_addc_co_u32_e32 v31, vcc, 0, v31, vcc
	global_load_dwordx4 v[30:33], v[30:31], off offset:2048 nt
	v_fmac_f32_e32 v19, v18, v107
	v_fmac_f32_e32 v19, v20, v108
	v_fmac_f32_e32 v19, v21, v106
	s_nop 1
	v_add_f32_dpp v18, v19, v19 quad_perm:[1,0,3,2] row_mask:0xf bank_mask:0xf bound_ctrl:1
	s_nop 1
	v_add_f32_dpp v18, v18, v18 quad_perm:[2,3,0,1] row_mask:0xf bank_mask:0xf bound_ctrl:1
	s_nop 1
	v_add_f32_dpp v18, v18, v18 row_ror:4 row_mask:0xf bank_mask:0xf bound_ctrl:1
	s_nop 1
	v_mov_b32_dpp v19, v18 row_ror:8 row_mask:0xf bank_mask:0xf bound_ctrl:1
	s_and_saveexec_b64 s[0:1], s[6:7]
	v_add_f32_e32 v18, v18, v19
	v_add_f32_e32 v18, v110, v18
	ds_write_b32 v99, v18
	s_or_b64 exec, exec, s[0:1]
	s_waitcnt vmcnt(13)
	v_mul_f32_e32 v11, v11, v109
	v_fmac_f32_e32 v11, v10, v107
	v_fmac_f32_e32 v11, v12, v108
	v_fmac_f32_e32 v11, v13, v106
	s_nop 1
	v_add_f32_dpp v10, v11, v11 quad_perm:[1,0,3,2] row_mask:0xf bank_mask:0xf bound_ctrl:1
	s_nop 1
	v_add_f32_dpp v10, v10, v10 quad_perm:[2,3,0,1] row_mask:0xf bank_mask:0xf bound_ctrl:1
	s_nop 1
	v_add_f32_dpp v10, v10, v10 row_ror:4 row_mask:0xf bank_mask:0xf bound_ctrl:1
	s_nop 1
	v_mov_b32_dpp v11, v10 row_ror:8 row_mask:0xf bank_mask:0xf bound_ctrl:1
	s_and_saveexec_b64 s[0:1], s[6:7]
	v_add_f32_e32 v10, v10, v11
	v_add_f32_e32 v10, v110, v10
	ds_write_b32 v99, v10 offset:16
	s_or_b64 exec, exec, s[0:1]
	s_waitcnt vmcnt(12)
; template <int NB>
; __device__ __forceinline__ void sb_decode_task(const Params& P, float* lds, int task) {
;     ...
;     for (int kb = 0; kb < NBT; ++kb) {
;         const float* np = (kb + 1 < NBT) ? Kp + (size_t)(4 * NB * (kb + 1)) * (SH * HD) : Vp;
; #pragma unroll
;         for (int i = 0; i < NB; ++i) nx[i] = *(const float4*)(np + (size_t)(4 * i + g) * (SH * HD));
; #pragma unroll
;         for (int i = 0; i < NB; ++i) { const int s = 4 * NB * kb + 4 * i + g;
;             float part = q0 * cur[i].x + q1 * cur[i].y + q2 * cur[i].z + q3 * cur[i].w; part = sum16(part);
;             if (c == 0) zl[s] = part + bias; }
	v_mul_f32_e32 v7, v7, v109
	v_fmac_f32_e32 v7, v6, v107
	v_fmac_f32_e32 v7, v8, v108
	v_fmac_f32_e32 v7, v9, v106
	s_nop 1
	v_add_f32_dpp v6, v7, v7 quad_perm:[1,0,3,2] row_mask:0xf bank_mask:0xf bound_ctrl:1
	s_nop 1
	v_add_f32_dpp v6, v6, v6 quad_perm:[2,3,0,1] row_mask:0xf bank_mask:0xf bound_ctrl:1
	s_nop 1
	v_add_f32_dpp v6, v6, v6 row_ror:4 row_mask:0xf bank_mask:0xf bound_ctrl:1
	s_nop 1
	v_mov_b32_dpp v7, v6 row_ror:8 row_mask:0xf bank_mask:0xf bound_ctrl:1
	s_and_saveexec_b64 s[0:1], s[6:7]
	v_add_f32_e32 v6, v6, v7
	v_add_f32_e32 v6, v110, v6
	ds_write_b32 v99, v6 offset:32
	s_or_b64 exec, exec, s[0:1]
	s_waitcnt vmcnt(6)
	v_mul_f32_e32 v3, v3, v109
	v_fmac_f32_e32 v3, v2, v107
	v_fmac_f32_e32 v3, v4, v108
	v_fmac_f32_e32 v3, v5, v106
	s_nop 1
	v_add_f32_dpp v2, v3, v3 quad_perm:[1,0,3,2] row_mask:0xf bank_mask:0xf bound_ctrl:1
	s_nop 1
	v_add_f32_dpp v2, v2, v2 quad_perm:[2,3,0,1] row_mask:0xf bank_mask:0xf bound_ctrl:1
	s_nop 1
	v_add_f32_dpp v2, v2, v2 row_ror:4 row_mask:0xf bank_mask:0xf bound_ctrl:1
	s_nop 1
	v_mov_b32_dpp v3, v2 row_ror:8 row_mask:0xf bank_mask:0xf bound_ctrl:1
	s_and_saveexec_b64 s[0:1], s[6:7]
	v_add_f32_e32 v2, v2, v3
	v_add_f32_e32 v2, v110, v2
	ds_write_b32 v99, v2 offset:48
	s_or_b64 exec, exec, s[0:1]
	v_mul_f32_e32 v2, v63, v109
	v_fmac_f32_e32 v2, v62, v107
	v_fmac_f32_e32 v2, v64, v108
	v_fmac_f32_e32 v2, v65, v106
	s_nop 1
	v_add_f32_dpp v2, v2, v2 quad_perm:[1,0,3,2] row_mask:0xf bank_mask:0xf bound_ctrl:1
	s_nop 1
	v_add_f32_dpp v2, v2, v2 quad_perm:[2,3,0,1] row_mask:0xf bank_mask:0xf bound_ctrl:1
	s_nop 1
	v_add_f32_dpp v2, v2, v2 row_ror:4 row_mask:0xf bank_mask:0xf bound_ctrl:1
	s_nop 1
	v_mov_b32_dpp v3, v2 row_ror:8 row_mask:0xf bank_mask:0xf bound_ctrl:1
	s_and_saveexec_b64 s[0:1], s[6:7]
	v_add_f32_e32 v2, v2, v3
	v_add_f32_e32 v2, v110, v2
	ds_write_b32 v99, v2 offset:64
	s_or_b64 exec, exec, s[0:1]
	v_mul_f32_e32 v2, v59, v109
	v_fmac_f32_e32 v2, v58, v107
	v_fmac_f32_e32 v2, v60, v108
	v_fmac_f32_e32 v2, v61, v106
	s_nop 1
	v_add_f32_dpp v2, v2, v2 quad_perm:[1,0,3,2] row_mask:0xf bank_mask:0xf bound_ctrl:1
	s_nop 1
	v_add_f32_dpp v2, v2, v2 quad_perm:[2,3,0,1] row_mask:0xf bank_mask:0xf bound_ctrl:1
	s_nop 1
	v_add_f32_dpp v2, v2, v2 row_ror:4 row_mask:0xf bank_mask:0xf bound_ctrl:1
	s_nop 1
	v_mov_b32_dpp v3, v2 row_ror:8 row_mask:0xf bank_mask:0xf bound_ctrl:1
	s_and_saveexec_b64 s[0:1], s[6:7]
	v_add_f32_e32 v2, v2, v3
	v_add_f32_e32 v2, v110, v2
	ds_write_b32 v99, v2 offset:80
	s_or_b64 exec, exec, s[0:1]
	v_mul_f32_e32 v2, v55, v109
	v_fmac_f32_e32 v2, v54, v107
	v_fmac_f32_e32 v2, v56, v108
	v_fmac_f32_e32 v2, v57, v106
	s_nop 1
	v_add_f32_dpp v2, v2, v2 quad_perm:[1,0,3,2] row_mask:0xf bank_mask:0xf bound_ctrl:1
	s_nop 1
	v_add_f32_dpp v2, v2, v2 quad_perm:[2,3,0,1] row_mask:0xf bank_mask:0xf bound_ctrl:1
	s_nop 1
	v_add_f32_dpp v2, v2, v2 row_ror:4 row_mask:0xf bank_mask:0xf bound_ctrl:1
	s_nop 1
	v_mov_b32_dpp v3, v2 row_ror:8 row_mask:0xf bank_mask:0xf bound_ctrl:1
	s_and_saveexec_b64 s[0:1], s[6:7]
	v_add_f32_e32 v2, v2, v3
	v_add_f32_e32 v2, v110, v2
	ds_write_b32 v99, v2 offset:96
	s_or_b64 exec, exec, s[0:1]
	v_mul_f32_e32 v2, v51, v109
	v_fmac_f32_e32 v2, v50, v107
	v_fmac_f32_e32 v2, v52, v108
	v_fmac_f32_e32 v2, v53, v106
	s_nop 1
	v_add_f32_dpp v2, v2, v2 quad_perm:[1,0,3,2] row_mask:0xf bank_mask:0xf bound_ctrl:1
	s_nop 1
	v_add_f32_dpp v2, v2, v2 quad_perm:[2,3,0,1] row_mask:0xf bank_mask:0xf bound_ctrl:1
	s_nop 1
	v_add_f32_dpp v2, v2, v2 row_ror:4 row_mask:0xf bank_mask:0xf bound_ctrl:1
	s_nop 1
	v_mov_b32_dpp v3, v2 row_ror:8 row_mask:0xf bank_mask:0xf bound_ctrl:1
	s_and_saveexec_b64 s[0:1], s[6:7]
	v_add_f32_e32 v2, v2, v3
	v_add_f32_e32 v2, v110, v2
	ds_write_b32 v99, v2 offset:112
	s_or_b64 exec, exec, s[0:1]
	s_mov_b64 s[0:1], 0x18000
	v_lshl_add_u64 v[2:3], v[70:71], 0, s[0:1]
	v_lshl_add_u64 v[4:5], v[2:3], 0, v[82:83]
	v_add_co_u32_e32 v6, vcc, 0x1000, v4
	v_mov_b32_e32 v93, v83
	s_nop 0
	v_addc_co_u32_e32 v7, vcc, 0, v5, vcc
	global_load_dwordx4 v[74:77], v[4:5], off nt
	global_load_dwordx4 v[66:69], v[6:7], off offset:2048 nt
	v_add_co_u32_e32 v6, vcc, 0x3000, v4
	v_lshl_add_u64 v[2:3], v[2:3], 0, v[92:93]
	s_nop 0
	v_addc_co_u32_e32 v7, vcc, 0, v5, vcc
	v_add_co_u32_e32 v8, vcc, s49, v4
	s_waitcnt vmcnt(6)
	v_mul_f32_e32 v47, v47, v109
	v_addc_co_u32_e32 v9, vcc, 0, v5, vcc
	global_load_dwordx4 v[58:61], v[6:7], off nt
	global_load_dwordx4 v[50:53], v[8:9], off offset:2048 nt
	v_add_co_u32_e32 v6, vcc, 0x7000, v4
	v_fmac_f32_e32 v47, v46, v107
	s_nop 0
	v_addc_co_u32_e32 v7, vcc, 0, v5, vcc
	global_load_dwordx4 v[18:21], v[2:3], off nt
	global_load_dwordx4 v[10:13], v[6:7], off offset:2048 nt
	v_add_co_u32_e32 v2, vcc, 0x9000, v4
	v_fmac_f32_e32 v47, v48, v108
	s_nop 0
	v_addc_co_u32_e32 v3, vcc, 0, v5, vcc
	v_add_co_u32_e32 v4, vcc, 0xa000, v4
	v_fmac_f32_e32 v47, v49, v106
	s_nop 0
	v_addc_co_u32_e32 v5, vcc, 0, v5, vcc
	global_load_dwordx4 v[6:9], v[2:3], off nt
	s_nop 0
	global_load_dwordx4 v[2:5], v[4:5], off offset:2048 nt
	v_add_f32_dpp v46, v47, v47 quad_perm:[1,0,3,2] row_mask:0xf bank_mask:0xf bound_ctrl:1
	s_nop 1
	v_add_f32_dpp v46, v46, v46 quad_perm:[2,3,0,1] row_mask:0xf bank_mask:0xf bound_ctrl:1
	s_nop 1
	v_add_f32_dpp v46, v46, v46 row_ror:4 row_mask:0xf bank_mask:0xf bound_ctrl:1
	s_nop 1
	v_mov_b32_dpp v47, v46 row_ror:8 row_mask:0xf bank_mask:0xf bound_ctrl:1
	s_and_saveexec_b64 s[0:1], s[6:7]
	v_add_f32_e32 v46, v46, v47
	v_add_f32_e32 v46, v110, v46
	ds_write_b32 v99, v46 offset:128
	s_or_b64 exec, exec, s[0:1]
	v_mul_f32_e32 v35, v35, v109
	v_fmac_f32_e32 v35, v34, v107
	v_fmac_f32_e32 v35, v36, v108
	v_fmac_f32_e32 v35, v37, v106
	s_nop 1
	v_add_f32_dpp v34, v35, v35 quad_perm:[1,0,3,2] row_mask:0xf bank_mask:0xf bound_ctrl:1
	s_nop 1
	v_add_f32_dpp v34, v34, v34 quad_perm:[2,3,0,1] row_mask:0xf bank_mask:0xf bound_ctrl:1
	s_nop 1
	v_add_f32_dpp v34, v34, v34 row_ror:4 row_mask:0xf bank_mask:0xf bound_ctrl:1
	s_nop 1
	v_mov_b32_dpp v35, v34 row_ror:8 row_mask:0xf bank_mask:0xf bound_ctrl:1
	s_and_saveexec_b64 s[0:1], s[6:7]
	v_add_f32_e32 v34, v34, v35
	v_add_f32_e32 v34, v110, v34
	ds_write_b32 v99, v34 offset:144
	s_or_b64 exec, exec, s[0:1]
	v_mul_f32_e32 v27, v27, v109
	v_fmac_f32_e32 v27, v26, v107
	v_fmac_f32_e32 v27, v28, v108
	v_fmac_f32_e32 v27, v29, v106
	s_nop 1
	v_add_f32_dpp v26, v27, v27 quad_perm:[1,0,3,2] row_mask:0xf bank_mask:0xf bound_ctrl:1
	s_nop 1
	v_add_f32_dpp v26, v26, v26 quad_perm:[2,3,0,1] row_mask:0xf bank_mask:0xf bound_ctrl:1
	s_nop 1
	v_add_f32_dpp v26, v26, v26 row_ror:4 row_mask:0xf bank_mask:0xf bound_ctrl:1
	s_nop 1
	v_mov_b32_dpp v27, v26 row_ror:8 row_mask:0xf bank_mask:0xf bound_ctrl:1
	s_and_saveexec_b64 s[0:1], s[6:7]
	v_add_f32_e32 v26, v26, v27
	v_add_f32_e32 v26, v110, v26
	ds_write_b32 v99, v26 offset:160
	s_or_b64 exec, exec, s[0:1]
	s_waitcnt vmcnt(11)
; template <int NB>
; __device__ __forceinline__ void sb_decode_task(const Params& P, float* lds, int task) {
;     ...
;     for (int kb = 0; kb < NBT; ++kb) {
;         const float* np = (kb + 1 < NBT) ? Kp + (size_t)(4 * NB * (kb + 1)) * (SH * HD) : Vp;
; #pragma unroll
;         for (int i = 0; i < NB; ++i) nx[i] = *(const float4*)(np + (size_t)(4 * i + g) * (SH * HD));
; #pragma unroll
;         for (int i = 0; i < NB; ++i) { const int s = 4 * NB * kb + 4 * i + g;
;             float part = q0 * cur[i].x + q1 * cur[i].y + q2 * cur[i].z + q3 * cur[i].w; part = sum16(part);
;             if (c == 0) zl[s] = part + bias; }
	v_mul_f32_e32 v15, v15, v109
	v_fmac_f32_e32 v15, v14, v107
	v_fmac_f32_e32 v15, v16, v108
	v_fmac_f32_e32 v15, v17, v106
	s_nop 1
	v_add_f32_dpp v14, v15, v15 quad_perm:[1,0,3,2] row_mask:0xf bank_mask:0xf bound_ctrl:1
	s_nop 1
	v_add_f32_dpp v14, v14, v14 quad_perm:[2,3,0,1] row_mask:0xf bank_mask:0xf bound_ctrl:1
	s_nop 1
	v_add_f32_dpp v14, v14, v14 row_ror:4 row_mask:0xf bank_mask:0xf bound_ctrl:1
	s_nop 1
	v_mov_b32_dpp v15, v14 row_ror:8 row_mask:0xf bank_mask:0xf bound_ctrl:1
	s_and_saveexec_b64 s[0:1], s[6:7]
	v_add_f32_e32 v14, v14, v15
	v_add_f32_e32 v14, v110, v14
	ds_write_b32 v99, v14 offset:176
	s_or_b64 exec, exec, s[0:1]
	v_mul_f32_e32 v14, v23, v109
	v_fmac_f32_e32 v14, v22, v107
	v_fmac_f32_e32 v14, v24, v108
	v_fmac_f32_e32 v14, v25, v106
	s_nop 1
	v_add_f32_dpp v14, v14, v14 quad_perm:[1,0,3,2] row_mask:0xf bank_mask:0xf bound_ctrl:1
	s_nop 1
	v_add_f32_dpp v14, v14, v14 quad_perm:[2,3,0,1] row_mask:0xf bank_mask:0xf bound_ctrl:1
	s_nop 1
	v_add_f32_dpp v14, v14, v14 row_ror:4 row_mask:0xf bank_mask:0xf bound_ctrl:1
	s_nop 1
	v_mov_b32_dpp v15, v14 row_ror:8 row_mask:0xf bank_mask:0xf bound_ctrl:1
	s_and_saveexec_b64 s[0:1], s[6:7]
	v_add_f32_e32 v14, v14, v15
	v_add_f32_e32 v14, v110, v14
	ds_write_b32 v99, v14 offset:192
	s_or_b64 exec, exec, s[0:1]
	s_waitcnt vmcnt(10)
	v_mul_f32_e32 v14, v39, v109
	v_fmac_f32_e32 v14, v38, v107
	v_fmac_f32_e32 v14, v40, v108
	v_fmac_f32_e32 v14, v41, v106
	s_nop 1
	v_add_f32_dpp v14, v14, v14 quad_perm:[1,0,3,2] row_mask:0xf bank_mask:0xf bound_ctrl:1
	s_nop 1
	v_add_f32_dpp v14, v14, v14 quad_perm:[2,3,0,1] row_mask:0xf bank_mask:0xf bound_ctrl:1
	s_nop 1
	v_add_f32_dpp v14, v14, v14 row_ror:4 row_mask:0xf bank_mask:0xf bound_ctrl:1
	s_nop 1
	v_mov_b32_dpp v15, v14 row_ror:8 row_mask:0xf bank_mask:0xf bound_ctrl:1
	s_and_saveexec_b64 s[0:1], s[6:7]
	v_add_f32_e32 v14, v14, v15
	v_add_f32_e32 v14, v110, v14
	ds_write_b32 v99, v14 offset:208
	s_or_b64 exec, exec, s[0:1]
	s_waitcnt vmcnt(9)
	v_mul_f32_e32 v14, v43, v109
	v_fmac_f32_e32 v14, v42, v107
	v_fmac_f32_e32 v14, v44, v108
	v_fmac_f32_e32 v14, v45, v106
	s_nop 1
	v_add_f32_dpp v14, v14, v14 quad_perm:[1,0,3,2] row_mask:0xf bank_mask:0xf bound_ctrl:1
	s_nop 1
	v_add_f32_dpp v14, v14, v14 quad_perm:[2,3,0,1] row_mask:0xf bank_mask:0xf bound_ctrl:1
	s_nop 1
	v_add_f32_dpp v14, v14, v14 row_ror:4 row_mask:0xf bank_mask:0xf bound_ctrl:1
	s_nop 1
	v_mov_b32_dpp v15, v14 row_ror:8 row_mask:0xf bank_mask:0xf bound_ctrl:1
	s_and_saveexec_b64 s[0:1], s[6:7]
	v_add_f32_e32 v14, v14, v15
	v_add_f32_e32 v14, v110, v14
	ds_write_b32 v99, v14 offset:224
	s_or_b64 exec, exec, s[0:1]
	s_waitcnt vmcnt(8)
	v_mul_f32_e32 v14, v31, v109
	v_fmac_f32_e32 v14, v30, v107
	v_fmac_f32_e32 v14, v32, v108
	v_fmac_f32_e32 v14, v33, v106
	s_nop 1
	v_add_f32_dpp v14, v14, v14 quad_perm:[1,0,3,2] row_mask:0xf bank_mask:0xf bound_ctrl:1
	s_nop 1
	v_add_f32_dpp v14, v14, v14 quad_perm:[2,3,0,1] row_mask:0xf bank_mask:0xf bound_ctrl:1
	s_nop 1
	v_add_f32_dpp v14, v14, v14 row_ror:4 row_mask:0xf bank_mask:0xf bound_ctrl:1
	s_nop 1
	v_mov_b32_dpp v15, v14 row_ror:8 row_mask:0xf bank_mask:0xf bound_ctrl:1
	s_and_saveexec_b64 s[0:1], s[6:7]
	v_add_f32_e32 v14, v14, v15
	v_add_f32_e32 v14, v110, v14
	ds_write_b32 v99, v14 offset:240
	s_or_b64 exec, exec, s[0:1]
	s_mov_b64 s[0:1], 0x24000
	v_lshl_add_u64 v[14:15], v[70:71], 0, s[0:1]
	v_lshl_add_u64 v[16:17], v[14:15], 0, v[82:83]
	v_add_co_u32_e32 v22, vcc, 0x1000, v16
	v_mov_b32_e32 v93, v83
	s_nop 0
	v_addc_co_u32_e32 v23, vcc, 0, v17, vcc
	global_load_dwordx4 v[78:81], v[16:17], off nt
	global_load_dwordx4 v[70:73], v[22:23], off offset:2048 nt
	v_add_co_u32_e32 v22, vcc, 0x3000, v16
	v_lshl_add_u64 v[14:15], v[14:15], 0, v[92:93]
	s_nop 0
	v_addc_co_u32_e32 v23, vcc, 0, v17, vcc
	v_add_co_u32_e32 v24, vcc, s49, v16
	s_nop 1
	v_addc_co_u32_e32 v25, vcc, 0, v17, vcc
	global_load_dwordx4 v[62:65], v[22:23], off nt
	global_load_dwordx4 v[54:57], v[24:25], off offset:2048 nt
	v_add_co_u32_e32 v22, vcc, 0x7000, v16
	s_nop 1
	v_addc_co_u32_e32 v23, vcc, 0, v17, vcc
	global_load_dwordx4 v[46:49], v[14:15], off nt
	global_load_dwordx4 v[42:45], v[22:23], off offset:2048 nt
	v_add_co_u32_e32 v14, vcc, 0x9000, v16
	s_nop 1
	v_addc_co_u32_e32 v15, vcc, 0, v17, vcc
	v_add_co_u32_e32 v16, vcc, 0xa000, v16
	s_nop 1
	v_addc_co_u32_e32 v17, vcc, 0, v17, vcc
	global_load_dwordx4 v[38:41], v[14:15], off nt
	global_load_dwordx4 v[34:37], v[16:17], off offset:2048 nt
	s_waitcnt vmcnt(15)
	v_mul_f32_e32 v14, v75, v109
	v_fmac_f32_e32 v14, v74, v107
	v_fmac_f32_e32 v14, v76, v108
	v_fmac_f32_e32 v14, v77, v106
	s_nop 1
	v_add_f32_dpp v14, v14, v14 quad_perm:[1,0,3,2] row_mask:0xf bank_mask:0xf bound_ctrl:1
	s_nop 1
	v_add_f32_dpp v14, v14, v14 quad_perm:[2,3,0,1] row_mask:0xf bank_mask:0xf bound_ctrl:1
	s_nop 1
	v_add_f32_dpp v14, v14, v14 row_ror:4 row_mask:0xf bank_mask:0xf bound_ctrl:1
	s_nop 1
	v_mov_b32_dpp v15, v14 row_ror:8 row_mask:0xf bank_mask:0xf bound_ctrl:1
	s_and_saveexec_b64 s[0:1], s[6:7]
	v_add_f32_e32 v14, v14, v15
	v_add_f32_e32 v14, v110, v14
	ds_write_b32 v99, v14 offset:256
	s_or_b64 exec, exec, s[0:1]
	s_waitcnt vmcnt(14)
	v_mul_f32_e32 v14, v67, v109
	v_fmac_f32_e32 v14, v66, v107
	v_fmac_f32_e32 v14, v68, v108
	v_fmac_f32_e32 v14, v69, v106
	s_nop 1
	v_add_f32_dpp v14, v14, v14 quad_perm:[1,0,3,2] row_mask:0xf bank_mask:0xf bound_ctrl:1
	s_nop 1
	v_add_f32_dpp v14, v14, v14 quad_perm:[2,3,0,1] row_mask:0xf bank_mask:0xf bound_ctrl:1
	s_nop 1
	v_add_f32_dpp v14, v14, v14 row_ror:4 row_mask:0xf bank_mask:0xf bound_ctrl:1
	s_nop 1
	v_mov_b32_dpp v15, v14 row_ror:8 row_mask:0xf bank_mask:0xf bound_ctrl:1
	s_and_saveexec_b64 s[0:1], s[6:7]
	v_add_f32_e32 v14, v14, v15
	v_add_f32_e32 v14, v110, v14
	ds_write_b32 v99, v14 offset:272
	s_or_b64 exec, exec, s[0:1]
	s_waitcnt vmcnt(13)
; template <int NB>
; __device__ __forceinline__ void sb_decode_task(const Params& P, float* lds, int task) {
;     ...
;     for (int kb = 0; kb < NBT; ++kb) {
;         const float* np = (kb + 1 < NBT) ? Kp + (size_t)(4 * NB * (kb + 1)) * (SH * HD) : Vp;
; #pragma unroll
;         for (int i = 0; i < NB; ++i) nx[i] = *(const float4*)(np + (size_t)(4 * i + g) * (SH * HD));
; #pragma unroll
;         for (int i = 0; i < NB; ++i) { const int s = 4 * NB * kb + 4 * i + g;
;             float part = q0 * cur[i].x + q1 * cur[i].y + q2 * cur[i].z + q3 * cur[i].w; part = sum16(part);
;             if (c == 0) zl[s] = part + bias; }
	v_mul_f32_e32 v14, v59, v109
	v_fmac_f32_e32 v14, v58, v107
	v_fmac_f32_e32 v14, v60, v108
	v_fmac_f32_e32 v14, v61, v106
	s_nop 1
	v_add_f32_dpp v14, v14, v14 quad_perm:[1,0,3,2] row_mask:0xf bank_mask:0xf bound_ctrl:1
	s_nop 1
	v_add_f32_dpp v14, v14, v14 quad_perm:[2,3,0,1] row_mask:0xf bank_mask:0xf bound_ctrl:1
	s_nop 1
	v_add_f32_dpp v14, v14, v14 row_ror:4 row_mask:0xf bank_mask:0xf bound_ctrl:1
	s_nop 1
	v_mov_b32_dpp v15, v14 row_ror:8 row_mask:0xf bank_mask:0xf bound_ctrl:1
	s_and_saveexec_b64 s[0:1], s[6:7]
	v_add_f32_e32 v14, v14, v15
	v_add_f32_e32 v14, v110, v14
	ds_write_b32 v99, v14 offset:288
	s_or_b64 exec, exec, s[0:1]
	s_waitcnt vmcnt(12)
	v_mul_f32_e32 v14, v51, v109
	v_fmac_f32_e32 v14, v50, v107
	v_fmac_f32_e32 v14, v52, v108
	v_fmac_f32_e32 v14, v53, v106
	s_nop 1
	v_add_f32_dpp v14, v14, v14 quad_perm:[1,0,3,2] row_mask:0xf bank_mask:0xf bound_ctrl:1
	s_nop 1
	v_add_f32_dpp v14, v14, v14 quad_perm:[2,3,0,1] row_mask:0xf bank_mask:0xf bound_ctrl:1
	s_nop 1
	v_add_f32_dpp v14, v14, v14 row_ror:4 row_mask:0xf bank_mask:0xf bound_ctrl:1
	s_nop 1
	v_mov_b32_dpp v15, v14 row_ror:8 row_mask:0xf bank_mask:0xf bound_ctrl:1
	s_and_saveexec_b64 s[0:1], s[6:7]
	v_add_f32_e32 v14, v14, v15
	v_add_f32_e32 v14, v110, v14
	ds_write_b32 v99, v14 offset:304
	s_or_b64 exec, exec, s[0:1]
	s_waitcnt vmcnt(11)
	v_mul_f32_e32 v14, v19, v109
	v_fmac_f32_e32 v14, v18, v107
	v_fmac_f32_e32 v14, v20, v108
	v_fmac_f32_e32 v14, v21, v106
	s_nop 1
	v_add_f32_dpp v14, v14, v14 quad_perm:[1,0,3,2] row_mask:0xf bank_mask:0xf bound_ctrl:1
	s_nop 1
	v_add_f32_dpp v14, v14, v14 quad_perm:[2,3,0,1] row_mask:0xf bank_mask:0xf bound_ctrl:1
	s_nop 1
	v_add_f32_dpp v14, v14, v14 row_ror:4 row_mask:0xf bank_mask:0xf bound_ctrl:1
	s_nop 1
	v_mov_b32_dpp v15, v14 row_ror:8 row_mask:0xf bank_mask:0xf bound_ctrl:1
	s_and_saveexec_b64 s[0:1], s[6:7]
	v_add_f32_e32 v14, v14, v15
	v_add_f32_e32 v14, v110, v14
	ds_write_b32 v99, v14 offset:320
	s_or_b64 exec, exec, s[0:1]
	s_waitcnt vmcnt(10)
	v_mul_f32_e32 v11, v11, v109
	v_fmac_f32_e32 v11, v10, v107
	v_fmac_f32_e32 v11, v12, v108
	v_fmac_f32_e32 v11, v13, v106
	s_nop 1
	v_add_f32_dpp v10, v11, v11 quad_perm:[1,0,3,2] row_mask:0xf bank_mask:0xf bound_ctrl:1
	s_nop 1
	v_add_f32_dpp v10, v10, v10 quad_perm:[2,3,0,1] row_mask:0xf bank_mask:0xf bound_ctrl:1
	s_nop 1
	v_add_f32_dpp v10, v10, v10 row_ror:4 row_mask:0xf bank_mask:0xf bound_ctrl:1
	s_nop 1
	v_mov_b32_dpp v11, v10 row_ror:8 row_mask:0xf bank_mask:0xf bound_ctrl:1
	s_and_saveexec_b64 s[0:1], s[6:7]
	v_add_f32_e32 v10, v10, v11
	v_add_f32_e32 v10, v110, v10
	ds_write_b32 v99, v10 offset:336
	s_or_b64 exec, exec, s[0:1]
	s_waitcnt vmcnt(9)
	v_mul_f32_e32 v7, v7, v109
	v_fmac_f32_e32 v7, v6, v107
	v_fmac_f32_e32 v7, v8, v108
	v_fmac_f32_e32 v7, v9, v106
	s_nop 1
	v_add_f32_dpp v6, v7, v7 quad_perm:[1,0,3,2] row_mask:0xf bank_mask:0xf bound_ctrl:1
	s_nop 1
	v_add_f32_dpp v6, v6, v6 quad_perm:[2,3,0,1] row_mask:0xf bank_mask:0xf bound_ctrl:1
	s_nop 1
	v_add_f32_dpp v6, v6, v6 row_ror:4 row_mask:0xf bank_mask:0xf bound_ctrl:1
	s_nop 1
	v_mov_b32_dpp v7, v6 row_ror:8 row_mask:0xf bank_mask:0xf bound_ctrl:1
	s_and_saveexec_b64 s[0:1], s[6:7]
	v_add_f32_e32 v6, v6, v7
	v_add_f32_e32 v6, v110, v6
	ds_write_b32 v99, v6 offset:352
	s_or_b64 exec, exec, s[0:1]
	s_waitcnt vmcnt(8)
	v_mul_f32_e32 v3, v3, v109
	v_fmac_f32_e32 v3, v2, v107
	v_fmac_f32_e32 v3, v4, v108
	v_fmac_f32_e32 v3, v5, v106
	s_nop 1
	v_add_f32_dpp v2, v3, v3 quad_perm:[1,0,3,2] row_mask:0xf bank_mask:0xf bound_ctrl:1
	s_nop 1
	v_add_f32_dpp v2, v2, v2 quad_perm:[2,3,0,1] row_mask:0xf bank_mask:0xf bound_ctrl:1
	s_nop 1
	v_add_f32_dpp v2, v2, v2 row_ror:4 row_mask:0xf bank_mask:0xf bound_ctrl:1
	s_nop 1
	v_mov_b32_dpp v3, v2 row_ror:8 row_mask:0xf bank_mask:0xf bound_ctrl:1
	s_and_saveexec_b64 s[0:1], s[6:7]
	v_add_f32_e32 v2, v2, v3
	v_add_f32_e32 v2, v110, v2
	ds_write_b32 v99, v2 offset:368
	s_or_b64 exec, exec, s[0:1]
	v_lshlrev_b64 v[2:3], 6, v[94:95]
	v_lshl_add_u64 v[6:7], v[2:3], 2, v[86:87]
	v_lshl_add_u64 v[50:51], v[6:7], 0, v[82:83]
	v_add_co_u32_e32 v2, vcc, 0x1000, v50
	v_mov_b32_e32 v93, v83
	s_nop 0
	v_addc_co_u32_e32 v3, vcc, 0, v51, vcc
	v_add_co_u32_e32 v8, vcc, 0x3000, v50
	v_lshl_add_u64 v[10:11], v[6:7], 0, v[92:93]
	s_nop 0
	v_addc_co_u32_e32 v9, vcc, 0, v51, vcc
	v_add_co_u32_e32 v14, vcc, s49, v50
	global_load_dwordx4 v[30:33], v[50:51], off nt
	s_nop 0
	global_load_dwordx4 v[2:5], v[2:3], off offset:2048 nt
	v_addc_co_u32_e32 v15, vcc, 0, v51, vcc
	v_add_co_u32_e32 v18, vcc, 0x7000, v50
	global_load_dwordx4 v[6:9], v[8:9], off nt
	s_nop 0
	global_load_dwordx4 v[10:13], v[10:11], off nt
	v_addc_co_u32_e32 v19, vcc, 0, v51, vcc
	v_add_co_u32_e32 v22, vcc, 0x9000, v50
	global_load_dwordx4 v[14:17], v[14:15], off offset:2048 nt
	s_nop 0
	global_load_dwordx4 v[18:21], v[18:19], off offset:2048 nt
	v_addc_co_u32_e32 v23, vcc, 0, v51, vcc
	v_add_co_u32_e32 v26, vcc, 0xa000, v50
	s_waitcnt vmcnt(13)
	v_mul_f32_e32 v52, v79, v109
	v_addc_co_u32_e32 v27, vcc, 0, v51, vcc
	global_load_dwordx4 v[22:25], v[22:23], off nt
	s_nop 0
	global_load_dwordx4 v[26:29], v[26:27], off offset:2048 nt
	v_fmac_f32_e32 v52, v78, v107
	v_fmac_f32_e32 v52, v80, v108
	v_fmac_f32_e32 v52, v81, v106
	s_nop 1
	v_add_f32_dpp v52, v52, v52 quad_perm:[1,0,3,2] row_mask:0xf bank_mask:0xf bound_ctrl:1
	s_nop 1
	v_add_f32_dpp v52, v52, v52 quad_perm:[2,3,0,1] row_mask:0xf bank_mask:0xf bound_ctrl:1
	s_nop 1
	v_add_f32_dpp v52, v52, v52 row_ror:4 row_mask:0xf bank_mask:0xf bound_ctrl:1
	s_nop 1
	v_mov_b32_dpp v53, v52 row_ror:8 row_mask:0xf bank_mask:0xf bound_ctrl:1
	s_and_saveexec_b64 s[0:1], s[6:7]
	v_add_f32_e32 v52, v52, v53
	v_add_f32_e32 v52, v110, v52
	ds_write_b32 v99, v52 offset:384
	s_or_b64 exec, exec, s[0:1]
	s_waitcnt vmcnt(14)
; template <int NB>
; __device__ __forceinline__ void sb_decode_task(const Params& P, float* lds, int task) {
;     ...
;     for (int kb = 0; kb < NBT; ++kb) {
;         const float* np = (kb + 1 < NBT) ? Kp + (size_t)(4 * NB * (kb + 1)) * (SH * HD) : Vp;
; #pragma unroll
;         for (int i = 0; i < NB; ++i) nx[i] = *(const float4*)(np + (size_t)(4 * i + g) * (SH * HD));
; #pragma unroll
;         for (int i = 0; i < NB; ++i) { const int s = 4 * NB * kb + 4 * i + g;
;             float part = q0 * cur[i].x + q1 * cur[i].y + q2 * cur[i].z + q3 * cur[i].w; part = sum16(part);
;             if (c == 0) zl[s] = part + bias; }
; #pragma unroll
;         for (int i = 0; i < NB; ++i) cur[i] = nx[i];
;     }
;     asm volatile("s_waitcnt lgkmcnt(0)" ::: "memory");
;     __builtin_amdgcn_wave_barrier();
;     const float z0 = zl[2 * lane], z1 = zl[2 * lane + 1];
	v_mul_f32_e32 v52, v71, v109
	v_fmac_f32_e32 v52, v70, v107
	v_fmac_f32_e32 v52, v72, v108
	v_fmac_f32_e32 v52, v73, v106
	s_nop 1
	v_add_f32_dpp v52, v52, v52 quad_perm:[1,0,3,2] row_mask:0xf bank_mask:0xf bound_ctrl:1
	s_nop 1
	v_add_f32_dpp v52, v52, v52 quad_perm:[2,3,0,1] row_mask:0xf bank_mask:0xf bound_ctrl:1
	s_nop 1
	v_add_f32_dpp v52, v52, v52 row_ror:4 row_mask:0xf bank_mask:0xf bound_ctrl:1
	s_nop 1
	v_mov_b32_dpp v53, v52 row_ror:8 row_mask:0xf bank_mask:0xf bound_ctrl:1
	s_and_saveexec_b64 s[0:1], s[6:7]
	v_add_f32_e32 v52, v52, v53
	v_add_f32_e32 v52, v110, v52
	ds_write_b32 v99, v52 offset:400
	s_or_b64 exec, exec, s[0:1]
	s_waitcnt vmcnt(13)
	v_mul_f32_e32 v52, v63, v109
	v_fmac_f32_e32 v52, v62, v107
	v_fmac_f32_e32 v52, v64, v108
	v_fmac_f32_e32 v52, v65, v106
	s_nop 1
	v_add_f32_dpp v52, v52, v52 quad_perm:[1,0,3,2] row_mask:0xf bank_mask:0xf bound_ctrl:1
	s_nop 1
	v_add_f32_dpp v52, v52, v52 quad_perm:[2,3,0,1] row_mask:0xf bank_mask:0xf bound_ctrl:1
	s_nop 1
	v_add_f32_dpp v52, v52, v52 row_ror:4 row_mask:0xf bank_mask:0xf bound_ctrl:1
	s_nop 1
	v_mov_b32_dpp v53, v52 row_ror:8 row_mask:0xf bank_mask:0xf bound_ctrl:1
	s_and_saveexec_b64 s[0:1], s[6:7]
	v_add_f32_e32 v52, v52, v53
	v_add_f32_e32 v52, v110, v52
	ds_write_b32 v99, v52 offset:416
	s_or_b64 exec, exec, s[0:1]
	s_waitcnt vmcnt(12)
	v_mul_f32_e32 v52, v55, v109
	v_fmac_f32_e32 v52, v54, v107
	v_fmac_f32_e32 v52, v56, v108
	v_fmac_f32_e32 v52, v57, v106
	s_nop 1
	v_add_f32_dpp v52, v52, v52 quad_perm:[1,0,3,2] row_mask:0xf bank_mask:0xf bound_ctrl:1
	s_nop 1
	v_add_f32_dpp v52, v52, v52 quad_perm:[2,3,0,1] row_mask:0xf bank_mask:0xf bound_ctrl:1
	s_nop 1
	v_add_f32_dpp v52, v52, v52 row_ror:4 row_mask:0xf bank_mask:0xf bound_ctrl:1
	s_nop 1
	v_mov_b32_dpp v53, v52 row_ror:8 row_mask:0xf bank_mask:0xf bound_ctrl:1
	s_and_saveexec_b64 s[0:1], s[6:7]
	v_add_f32_e32 v52, v52, v53
	v_add_f32_e32 v52, v110, v52
	ds_write_b32 v99, v52 offset:432
	s_or_b64 exec, exec, s[0:1]
	s_waitcnt vmcnt(11)
	v_mul_f32_e32 v47, v47, v109
	v_fmac_f32_e32 v47, v46, v107
	v_fmac_f32_e32 v47, v48, v108
	v_fmac_f32_e32 v47, v49, v106
	s_nop 1
	v_add_f32_dpp v46, v47, v47 quad_perm:[1,0,3,2] row_mask:0xf bank_mask:0xf bound_ctrl:1
	s_nop 1
	v_add_f32_dpp v46, v46, v46 quad_perm:[2,3,0,1] row_mask:0xf bank_mask:0xf bound_ctrl:1
	s_nop 1
	v_add_f32_dpp v46, v46, v46 row_ror:4 row_mask:0xf bank_mask:0xf bound_ctrl:1
	s_nop 1
	v_mov_b32_dpp v47, v46 row_ror:8 row_mask:0xf bank_mask:0xf bound_ctrl:1
	s_and_saveexec_b64 s[0:1], s[6:7]
	v_add_f32_e32 v46, v46, v47
	v_add_f32_e32 v46, v110, v46
	ds_write_b32 v99, v46 offset:448
	s_or_b64 exec, exec, s[0:1]
	s_waitcnt vmcnt(10)
	v_mul_f32_e32 v43, v43, v109
	v_fmac_f32_e32 v43, v42, v107
	v_fmac_f32_e32 v43, v44, v108
	v_fmac_f32_e32 v43, v45, v106
	s_nop 1
	v_add_f32_dpp v42, v43, v43 quad_perm:[1,0,3,2] row_mask:0xf bank_mask:0xf bound_ctrl:1
	s_nop 1
	v_add_f32_dpp v42, v42, v42 quad_perm:[2,3,0,1] row_mask:0xf bank_mask:0xf bound_ctrl:1
	s_nop 1
	v_add_f32_dpp v42, v42, v42 row_ror:4 row_mask:0xf bank_mask:0xf bound_ctrl:1
	s_nop 1
	v_mov_b32_dpp v43, v42 row_ror:8 row_mask:0xf bank_mask:0xf bound_ctrl:1
	s_and_saveexec_b64 s[0:1], s[6:7]
	v_add_f32_e32 v42, v42, v43
	v_add_f32_e32 v42, v110, v42
	ds_write_b32 v99, v42 offset:464
	s_or_b64 exec, exec, s[0:1]
	s_waitcnt vmcnt(9)
	v_mul_f32_e32 v39, v39, v109
	v_fmac_f32_e32 v39, v38, v107
	v_fmac_f32_e32 v39, v40, v108
	v_fmac_f32_e32 v39, v41, v106
	s_nop 1
	v_add_f32_dpp v38, v39, v39 quad_perm:[1,0,3,2] row_mask:0xf bank_mask:0xf bound_ctrl:1
	s_nop 1
	v_add_f32_dpp v38, v38, v38 quad_perm:[2,3,0,1] row_mask:0xf bank_mask:0xf bound_ctrl:1
	s_nop 1
	v_add_f32_dpp v38, v38, v38 row_ror:4 row_mask:0xf bank_mask:0xf bound_ctrl:1
	s_nop 1
	v_mov_b32_dpp v39, v38 row_ror:8 row_mask:0xf bank_mask:0xf bound_ctrl:1
	s_and_saveexec_b64 s[0:1], s[6:7]
	v_add_f32_e32 v38, v38, v39
	v_add_f32_e32 v38, v110, v38
	ds_write_b32 v99, v38 offset:480
	s_or_b64 exec, exec, s[0:1]
	s_waitcnt vmcnt(8)
	v_mul_f32_e32 v35, v35, v109
	v_fmac_f32_e32 v35, v34, v107
	v_fmac_f32_e32 v35, v36, v108
	v_fmac_f32_e32 v35, v37, v106
	s_nop 1
	v_add_f32_dpp v34, v35, v35 quad_perm:[1,0,3,2] row_mask:0xf bank_mask:0xf bound_ctrl:1
	s_nop 1
	v_add_f32_dpp v34, v34, v34 quad_perm:[2,3,0,1] row_mask:0xf bank_mask:0xf bound_ctrl:1
	s_nop 1
	v_add_f32_dpp v34, v34, v34 row_ror:4 row_mask:0xf bank_mask:0xf bound_ctrl:1
	s_nop 1
	v_mov_b32_dpp v35, v34 row_ror:8 row_mask:0xf bank_mask:0xf bound_ctrl:1
	s_and_saveexec_b64 s[0:1], s[6:7]
	v_add_f32_e32 v34, v34, v35
	v_add_f32_e32 v34, v110, v34
	ds_write_b32 v99, v34 offset:496
	s_or_b64 exec, exec, s[0:1]
	s_waitcnt lgkmcnt(0)
	ds_read_b64 v[34:35], v100
	s_waitcnt lgkmcnt(0)
; __device__ __forceinline__ float softplus2_(float z2) { return fmaxf(z2, 0.f) + log1pf(exp2f(-fabsf(z2))) * LOG2E; }
; template <int NB>
; __device__ __forceinline__ void sb_decode_task(const Params& P, float* lds, int task) {
;     ...
;     const float z0 = zl[2 * lane], z1 = zl[2 * lane + 1];
;     const float sp0 = softplus2_(z0), sp1 = softplus2_(z1);
	v_cmp_gt_f32_e64 vcc, |v34|, s97
	s_nop 1
	v_cndmask_b32_e32 v37, 0, v103, vcc
	v_sub_f32_e64 v37, v37, |v34|
	v_exp_f32_e32 v37, v37
	v_max_f32_e32 v36, v34, v34
	v_max_f32_e32 v38, 0, v36
	v_cndmask_b32_e32 v36, 0, v102, vcc
	v_ldexp_f32 v39, v37, v36
	v_add_f32_e32 v40, 1.0, v39
	v_add_f32_e32 v36, -1.0, v40
	v_sub_f32_e32 v37, v36, v40
	v_add_f32_e32 v37, 1.0, v37
	v_sub_f32_e32 v36, v39, v36
	v_add_f32_e32 v41, v36, v37
	v_frexp_mant_f32_e32 v36, v40
	v_cmp_gt_f32_e32 vcc, s47, v36
	v_cvt_f64_f32_e32 v[36:37], v40
	v_frexp_exp_i32_f64_e32 v36, v[36:37]
	v_subbrev_co_u32_e32 v36, vcc, 0, v36, vcc
	v_sub_u32_e32 v37, 0, v36
	v_ldexp_f32 v40, v40, v37
	v_ldexp_f32 v37, v41, v37
	v_add_f32_e32 v41, -1.0, v40
	v_add_f32_e32 v42, 1.0, v41
	v_sub_f32_e32 v42, v40, v42
	v_add_f32_e32 v42, v37, v42
	v_add_f32_e32 v43, v41, v42
	v_sub_f32_e32 v41, v41, v43
	v_add_f32_e32 v41, v42, v41
	v_add_f32_e32 v42, 1.0, v40
	v_add_f32_e32 v44, -1.0, v42
	v_sub_f32_e32 v40, v40, v44
	v_add_f32_e32 v37, v37, v40
	v_add_f32_e32 v40, v42, v37
	v_sub_f32_e32 v42, v42, v40
	v_add_f32_e32 v37, v37, v42
	v_rcp_f32_e32 v42, v40
	v_cvt_f32_i32_e32 v36, v36
	v_cmp_neq_f32_e32 vcc, s46, v39
	v_mul_f32_e32 v44, v43, v42
	v_mul_f32_e32 v45, v40, v44
	v_fma_f32 v46, v44, v40, -v45
	v_fmac_f32_e32 v46, v44, v37
	v_add_f32_e32 v47, v45, v46
	v_sub_f32_e32 v48, v43, v47
	v_sub_f32_e32 v43, v43, v48
	v_sub_f32_e32 v45, v47, v45
	v_sub_f32_e32 v43, v43, v47
	v_add_f32_e32 v41, v41, v43
	v_sub_f32_e32 v43, v45, v46
	v_add_f32_e32 v41, v43, v41
	v_add_f32_e32 v43, v48, v41
	v_mul_f32_e32 v45, v42, v43
	v_mul_f32_e32 v46, v40, v45
	v_fma_f32 v40, v45, v40, -v46
	v_fmac_f32_e32 v40, v45, v37
	v_sub_f32_e32 v37, v48, v43
	v_add_f32_e32 v37, v41, v37
	v_add_f32_e32 v41, v46, v40
	v_sub_f32_e32 v47, v43, v41
	v_sub_f32_e32 v43, v43, v47
	v_sub_f32_e32 v46, v41, v46
	v_sub_f32_e32 v41, v43, v41
	v_add_f32_e32 v37, v37, v41
	v_sub_f32_e32 v40, v46, v40
	v_add_f32_e32 v37, v40, v37
	v_add_f32_e32 v40, v44, v45
	v_add_f32_e32 v37, v47, v37
	v_sub_f32_e32 v41, v40, v44
	v_mul_f32_e32 v37, v42, v37
	v_sub_f32_e32 v41, v45, v41
	v_add_f32_e32 v37, v41, v37
	v_mul_f32_e32 v44, 0x3f317218, v36
	v_add_f32_e32 v41, v40, v37
	v_fma_f32 v45, v36, s95, -v44
	v_mul_f32_e32 v42, v41, v41
	v_fmac_f32_e32 v45, 0xb102e308, v36
	v_sub_f32_e32 v36, v41, v40
	v_fmamk_f32 v43, v42, 0x3e9b6dac, v1
	v_sub_f32_e32 v36, v37, v36
	v_add_f32_e32 v37, v44, v45
	v_fmaak_f32 v43, v42, v43, 0x3f2aaada
	v_sub_f32_e32 v40, v37, v44
	v_ldexp_f32 v44, v41, 1
	v_mul_f32_e32 v41, v41, v42
	v_mul_f32_e32 v41, v41, v43
	v_add_f32_e32 v42, v44, v41
	v_sub_f32_e32 v43, v42, v44
	v_ldexp_f32 v36, v36, 1
	v_sub_f32_e32 v41, v41, v43
	v_add_f32_e32 v36, v36, v41
	v_add_f32_e32 v41, v42, v36
	v_sub_f32_e32 v42, v41, v42
	v_sub_f32_e32 v36, v36, v42
	v_add_f32_e32 v42, v37, v41
	v_sub_f32_e32 v43, v42, v37
	v_sub_f32_e32 v44, v42, v43
	v_sub_f32_e32 v40, v45, v40
	v_sub_f32_e32 v37, v37, v44
	v_sub_f32_e32 v41, v41, v43
	v_add_f32_e32 v37, v41, v37
	v_add_f32_e32 v41, v40, v36
	v_sub_f32_e32 v43, v41, v40
	v_sub_f32_e32 v44, v41, v43
	v_sub_f32_e32 v40, v40, v44
	v_sub_f32_e32 v36, v36, v43
	v_add_f32_e32 v37, v41, v37
	v_add_f32_e32 v36, v36, v40
	v_add_f32_e32 v40, v42, v37
	v_sub_f32_e32 v41, v40, v42
	v_sub_f32_e32 v37, v37, v41
	v_add_f32_e32 v36, v36, v37
	v_add_f32_e32 v36, v40, v36
	v_cndmask_b32_e32 v36, v104, v36, vcc
	v_cmp_lt_f32_e64 vcc, |v39|, s45
	s_nop 1
	v_cndmask_b32_e32 v36, v36, v39, vcc
	v_cmp_gt_f32_e64 vcc, |v35|, s97
	v_fmac_f32_e32 v38, 0x3fb8aa3b, v36
	v_max_f32_e32 v36, v35, v35
	v_cndmask_b32_e32 v37, 0, v103, vcc
	v_sub_f32_e64 v37, v37, |v35|
	v_exp_f32_e32 v37, v37
	v_max_f32_e32 v39, 0, v36
	v_cndmask_b32_e32 v36, 0, v102, vcc
	v_sub_f32_e32 v34, v34, v38
	v_ldexp_f32 v40, v37, v36
	v_add_f32_e32 v41, 1.0, v40
	v_add_f32_e32 v36, -1.0, v41
	v_sub_f32_e32 v37, v36, v41
	v_add_f32_e32 v37, 1.0, v37
	v_sub_f32_e32 v36, v40, v36
	v_add_f32_e32 v42, v36, v37
	v_frexp_mant_f32_e32 v36, v41
	v_cmp_gt_f32_e32 vcc, s47, v36
	v_cvt_f64_f32_e32 v[36:37], v41
	v_frexp_exp_i32_f64_e32 v36, v[36:37]
	v_subbrev_co_u32_e32 v36, vcc, 0, v36, vcc
	v_sub_u32_e32 v37, 0, v36
	v_ldexp_f32 v41, v41, v37
	v_ldexp_f32 v37, v42, v37
	v_add_f32_e32 v42, -1.0, v41
	v_add_f32_e32 v43, 1.0, v42
	v_sub_f32_e32 v43, v41, v43
	v_add_f32_e32 v43, v37, v43
	v_add_f32_e32 v44, v42, v43
	v_sub_f32_e32 v42, v42, v44
	v_add_f32_e32 v42, v43, v42
	v_add_f32_e32 v43, 1.0, v41
	v_add_f32_e32 v45, -1.0, v43
	v_sub_f32_e32 v41, v41, v45
	v_add_f32_e32 v37, v37, v41
	v_add_f32_e32 v41, v43, v37
	v_sub_f32_e32 v43, v43, v41
	v_add_f32_e32 v37, v37, v43
	v_rcp_f32_e32 v43, v41
	v_cvt_f32_i32_e32 v36, v36
	v_cmp_neq_f32_e32 vcc, s46, v40
	v_mul_f32_e32 v45, v44, v43
	v_mul_f32_e32 v46, v41, v45
	v_fma_f32 v47, v45, v41, -v46
	v_fmac_f32_e32 v47, v45, v37
	v_add_f32_e32 v48, v46, v47
	v_sub_f32_e32 v49, v44, v48
	v_sub_f32_e32 v44, v44, v49
	v_sub_f32_e32 v46, v48, v46
	v_sub_f32_e32 v44, v44, v48
	v_add_f32_e32 v42, v42, v44
	v_sub_f32_e32 v44, v46, v47
	v_add_f32_e32 v42, v44, v42
	v_add_f32_e32 v44, v49, v42
	v_mul_f32_e32 v46, v43, v44
	v_mul_f32_e32 v47, v41, v46
	v_fma_f32 v41, v46, v41, -v47
	v_fmac_f32_e32 v41, v46, v37
	v_sub_f32_e32 v37, v49, v44
	v_add_f32_e32 v37, v42, v37
	v_add_f32_e32 v42, v47, v41
	v_sub_f32_e32 v48, v44, v42
	v_sub_f32_e32 v44, v44, v48
	v_sub_f32_e32 v47, v42, v47
	v_sub_f32_e32 v42, v44, v42
	v_add_f32_e32 v37, v37, v42
	v_sub_f32_e32 v41, v47, v41
	v_add_f32_e32 v37, v41, v37
	v_add_f32_e32 v41, v45, v46
	v_add_f32_e32 v37, v48, v37
	v_sub_f32_e32 v42, v41, v45
	v_mul_f32_e32 v37, v43, v37
; __device__ __forceinline__ float softplus2_(float z2) { return fmaxf(z2, 0.f) + log1pf(exp2f(-fabsf(z2))) * LOG2E; }
; template <int NB>
; __device__ __forceinline__ void sb_decode_task(const Params& P, float* lds, int task) {
;     ...
;     const float sp0 = softplus2_(z0), sp1 = softplus2_(z1);
;     float incl = sp0 + sp1;
; #pragma unroll
;     for (int off = 1; off < 64; off <<= 1) { const float t = __shfl_down(incl, off); if (lane + off < 64) incl += t; }
;     const float excl = incl - (sp0 + sp1);
;     wl[2 * lane] = exp2f(z0 - sp0 - (excl + sp1));
;     wl[2 * lane + 1] = exp2f(z1 - sp1 - excl);
;     const float Ltot = __shfl(incl, 0);
;     asm volatile("s_waitcnt lgkmcnt(0)" ::: "memory");
;     __builtin_amdgcn_wave_barrier();
;     float4 o4 = make_float4(0.f, 0.f, 0.f, 0.f);
; #pragma unroll
;     for (int vb = 0; vb < NBT; ++vb) {
;         if (vb + 1 < NBT) {
; #pragma unroll
;             for (int i = 0; i < NB; ++i) nx[i] = *(const float4*)(Vp + (size_t)(4 * NB * (vb + 1) + 4 * i + g) * (SH * HD)); }
; #pragma unroll
;         for (int i = 0; i < NB; ++i) { const float w = wl[4 * NB * vb + 4 * i + g]; o4.x += w * cur[i].x; o4.y += w * cur[i].y; o4.z += w * cur[i].z; o4.w += w * cur[i].w; }
	v_sub_f32_e32 v42, v46, v42
	v_add_f32_e32 v37, v42, v37
	v_mul_f32_e32 v45, 0x3f317218, v36
	v_add_f32_e32 v42, v41, v37
	v_fma_f32 v46, v36, s95, -v45
	v_mul_f32_e32 v43, v42, v42
	v_fmac_f32_e32 v46, 0xb102e308, v36
	v_sub_f32_e32 v36, v42, v41
	v_fmamk_f32 v44, v43, 0x3e9b6dac, v1
	v_sub_f32_e32 v36, v37, v36
	v_add_f32_e32 v37, v45, v46
	v_fmaak_f32 v44, v43, v44, 0x3f2aaada
	v_sub_f32_e32 v41, v37, v45
	v_ldexp_f32 v45, v42, 1
	v_mul_f32_e32 v42, v42, v43
	v_mul_f32_e32 v42, v42, v44
	v_add_f32_e32 v43, v45, v42
	v_sub_f32_e32 v44, v43, v45
	v_ldexp_f32 v36, v36, 1
	v_sub_f32_e32 v42, v42, v44
	v_add_f32_e32 v36, v36, v42
	v_add_f32_e32 v42, v43, v36
	v_sub_f32_e32 v43, v42, v43
	v_sub_f32_e32 v36, v36, v43
	v_add_f32_e32 v43, v37, v42
	v_sub_f32_e32 v44, v43, v37
	v_sub_f32_e32 v45, v43, v44
	v_sub_f32_e32 v41, v46, v41
	v_sub_f32_e32 v37, v37, v45
	v_sub_f32_e32 v42, v42, v44
	v_add_f32_e32 v37, v42, v37
	v_add_f32_e32 v42, v41, v36
	v_sub_f32_e32 v44, v42, v41
	v_sub_f32_e32 v45, v42, v44
	v_sub_f32_e32 v41, v41, v45
	v_sub_f32_e32 v36, v36, v44
	v_add_f32_e32 v37, v42, v37
	v_add_f32_e32 v36, v36, v41
	v_add_f32_e32 v41, v43, v37
	v_sub_f32_e32 v42, v41, v43
	v_sub_f32_e32 v37, v37, v42
	v_add_f32_e32 v36, v36, v37
	v_add_f32_e32 v36, v41, v36
	v_cndmask_b32_e32 v36, v104, v36, vcc
	v_cmp_lt_f32_e64 vcc, |v40|, s45
	v_and_b32_e32 v37, 63, v105
	s_nop 0
	v_cndmask_b32_e32 v36, v36, v40, vcc
	v_cmp_ne_u32_e32 vcc, 63, v37
	v_fmac_f32_e32 v39, 0x3fb8aa3b, v36
	v_add_f32_e32 v36, v38, v39
	v_addc_co_u32_e32 v40, vcc, 0, v105, vcc
	v_lshlrev_b32_e32 v108, 2, v40
	ds_bpermute_b32 v40, v108, v36
	v_cmp_gt_u32_e32 vcc, 62, v37
	v_sub_f32_e32 v35, v35, v39
	s_waitcnt lgkmcnt(0)
	v_add_f32_e32 v40, v36, v40
	v_cndmask_b32_e64 v41, 0, 2, vcc
	v_cndmask_b32_e64 v40, v40, v36, s[8:9]
	v_add_lshl_u32 v109, v41, v105, 2
	ds_bpermute_b32 v41, v109, v40
	v_cmp_gt_u32_e32 vcc, 60, v37
	s_waitcnt lgkmcnt(0)
	v_add_f32_e32 v41, v40, v41
	v_cndmask_b32_e64 v40, v40, v41, s[10:11]
	v_cndmask_b32_e64 v41, 0, 4, vcc
	v_add_lshl_u32 v110, v41, v105, 2
	ds_bpermute_b32 v41, v110, v40
	v_cmp_gt_u32_e32 vcc, 56, v37
	s_waitcnt lgkmcnt(0)
	v_add_f32_e32 v41, v40, v41
	v_cndmask_b32_e64 v40, v40, v41, s[12:13]
	v_cndmask_b32_e64 v41, 0, 8, vcc
	v_add_lshl_u32 v111, v41, v105, 2
	ds_bpermute_b32 v41, v111, v40
	v_cmp_gt_u32_e32 vcc, 48, v37
	s_waitcnt lgkmcnt(0)
	v_add_f32_e32 v41, v40, v41
	v_cndmask_b32_e64 v37, 0, 16, vcc
	v_cndmask_b32_e64 v40, v40, v41, s[14:15]
	v_add_lshl_u32 v112, v37, v105, 2
	ds_bpermute_b32 v37, v112, v40
	s_waitcnt lgkmcnt(0)
	v_add_f32_e32 v37, v40, v37
	v_cndmask_b32_e64 v37, v40, v37, s[16:17]
	v_lshlrev_b32_e32 v40, 2, v105
	v_or_b32_e32 v113, 0x80, v40
	ds_bpermute_b32 v41, v113, v37
	v_and_b32_e32 v106, 0x100, v40
	s_waitcnt lgkmcnt(0)
	v_add_f32_e32 v41, v37, v41
	v_cndmask_b32_e64 v44, v37, v41, s[18:19]
	v_sub_f32_e32 v36, v44, v36
	v_add_f32_e32 v37, v39, v36
	v_sub_f32_e32 v34, v34, v37
	v_cmp_gt_f32_e32 vcc, s24, v34
	v_sub_f32_e32 v35, v35, v36
	s_nop 0
	v_cndmask_b32_e32 v37, 0, v103, vcc
	v_add_f32_e32 v34, v34, v37
	v_cndmask_b32_e32 v37, 0, v102, vcc
	v_cmp_gt_f32_e32 vcc, s24, v35
	v_exp_f32_e32 v34, v34
	s_nop 0
	v_cndmask_b32_e32 v36, 0, v103, vcc
	v_add_f32_e32 v35, v35, v36
	v_exp_f32_e32 v35, v35
	v_cndmask_b32_e32 v36, 0, v102, vcc
	v_ldexp_f32 v34, v34, v37
	v_ldexp_f32 v35, v35, v36
	ds_write_b64 v100, v[34:35] offset:512
	s_waitcnt lgkmcnt(0)
	ds_read2_b32 v[34:35], v99 offset0:128 offset1:132
	ds_read2_b32 v[42:43], v99 offset0:136 offset1:140
	ds_read2_b32 v[66:67], v99 offset0:144 offset1:148
	ds_read2_b32 v[68:69], v99 offset0:152 offset1:156
	ds_read2_b32 v[74:75], v99 offset0:160 offset1:164
	ds_read2_b32 v[76:77], v99 offset0:168 offset1:172
	ds_read2_b32 v[38:39], v99 offset0:176 offset1:180
	ds_read2_b32 v[40:41], v99 offset0:184 offset1:188
	s_waitcnt vmcnt(7) lgkmcnt(7)
	v_pk_fma_f32 v[70:71], v[30:31], v[34:35], 0 op_sel_hi:[1,0,0]
	v_add_co_u32_e32 v30, vcc, s25, v50
	v_pk_fma_f32 v[72:73], v[32:33], v[34:35], 0 op_sel_hi:[1,0,0]
	s_nop 0
	v_addc_co_u32_e32 v31, vcc, 0, v51, vcc
	v_add_co_u32_e32 v34, vcc, s43, v50
	v_mov_b32_e32 v64, v35
	s_nop 0
	v_addc_co_u32_e32 v35, vcc, 0, v51, vcc
	v_add_co_u32_e32 v46, vcc, s44, v50
	s_waitcnt vmcnt(6)
	v_pk_fma_f32 v[2:3], v[2:3], v[64:65], v[70:71] op_sel_hi:[1,0,1]
	v_addc_co_u32_e32 v47, vcc, 0, v51, vcc
	v_add_co_u32_e32 v52, vcc, s26, v50
	global_load_dwordx4 v[46:49], v[46:47], off nt
	s_nop 0
	v_addc_co_u32_e32 v53, vcc, 0, v51, vcc
	v_add_co_u32_e32 v56, vcc, s27, v50
	global_load_dwordx4 v[52:55], v[52:53], off offset:2048 nt
	s_nop 0
	v_addc_co_u32_e32 v57, vcc, 0, v51, vcc
	v_add_co_u32_e32 v60, vcc, s28, v50
	global_load_dwordx4 v[56:59], v[56:57], off nt
	s_nop 0
	v_addc_co_u32_e32 v61, vcc, 0, v51, vcc
	global_load_dwordx4 v[60:63], v[60:61], off offset:2048 nt
	s_waitcnt lgkmcnt(6)
	v_mov_b32_e32 v78, v43
	s_waitcnt vmcnt(9)
	v_pk_fma_f32 v[2:3], v[6:7], v[42:43], v[2:3] op_sel_hi:[1,0,1]
	s_waitcnt lgkmcnt(5)
	v_mov_b32_e32 v80, v67
	s_waitcnt vmcnt(7)
	v_pk_fma_f32 v[2:3], v[14:15], v[78:79], v[2:3] op_sel_hi:[1,0,1]
	s_waitcnt lgkmcnt(4)
	v_mov_b32_e32 v94, v69
	v_pk_fma_f32 v[2:3], v[10:11], v[66:67], v[2:3] op_sel_hi:[1,0,1]
	s_waitcnt lgkmcnt(3)
	v_mov_b32_e32 v10, v75
	s_waitcnt vmcnt(6)
	v_pk_fma_f32 v[2:3], v[18:19], v[80:81], v[2:3] op_sel_hi:[1,0,1]
	s_waitcnt lgkmcnt(2)
	v_mov_b32_e32 v14, v77
	s_waitcnt vmcnt(5)
	v_pk_fma_f32 v[2:3], v[22:23], v[68:69], v[2:3] op_sel_hi:[1,0,1]
	global_load_dwordx4 v[30:33], v[30:31], off nt
	s_waitcnt vmcnt(5)
; template <int NB>
; __device__ __forceinline__ void sb_decode_task(const Params& P, float* lds, int task) {
;     ...
; #pragma unroll
;     for (int vb = 0; vb < NBT; ++vb) {
;         if (vb + 1 < NBT) {
; #pragma unroll
;             for (int i = 0; i < NB; ++i) nx[i] = *(const float4*)(Vp + (size_t)(4 * NB * (vb + 1) + 4 * i + g) * (SH * HD)); }
; #pragma unroll
;         for (int i = 0; i < NB; ++i) { const float w = wl[4 * NB * vb + 4 * i + g]; o4.x += w * cur[i].x; o4.y += w * cur[i].y; o4.z += w * cur[i].z; o4.w += w * cur[i].w; }
; #pragma unroll
;         for (int i = 0; i < NB; ++i) cur[i] = nx[i];
	v_pk_fma_f32 v[2:3], v[26:27], v[94:95], v[2:3] op_sel_hi:[1,0,1]
	global_load_dwordx4 v[34:37], v[34:35], off offset:2048 nt
	s_waitcnt vmcnt(5)
	v_pk_fma_f32 v[2:3], v[46:47], v[74:75], v[2:3] op_sel_hi:[1,0,1]
	s_waitcnt vmcnt(4)
	v_pk_fma_f32 v[2:3], v[52:53], v[10:11], v[2:3] op_sel_hi:[1,0,1]
	s_waitcnt vmcnt(3)
	v_pk_fma_f32 v[2:3], v[56:57], v[76:77], v[2:3] op_sel_hi:[1,0,1]
	s_waitcnt vmcnt(2)
	v_pk_fma_f32 v[6:7], v[60:61], v[14:15], v[2:3] op_sel_hi:[1,0,1]
	v_pk_fma_f32 v[2:3], v[4:5], v[64:65], v[72:73] op_sel_hi:[1,0,1]
	v_add_co_u32_e32 v4, vcc, s29, v50
	v_pk_fma_f32 v[2:3], v[8:9], v[42:43], v[2:3] op_sel_hi:[1,0,1]
	s_nop 0
	v_addc_co_u32_e32 v5, vcc, 0, v51, vcc
	v_pk_fma_f32 v[2:3], v[16:17], v[78:79], v[2:3] op_sel_hi:[1,0,1]
	s_waitcnt lgkmcnt(0)
	v_mov_b32_e32 v42, v41
	v_pk_fma_f32 v[2:3], v[12:13], v[66:67], v[2:3] op_sel_hi:[1,0,1]
	s_waitcnt vmcnt(1)
	v_pk_fma_f32 v[6:7], v[30:31], v[38:39], v[6:7] op_sel_hi:[1,0,1]
	v_pk_fma_f32 v[2:3], v[20:21], v[80:81], v[2:3] op_sel_hi:[1,0,1]
	s_nop 0
	v_pk_fma_f32 v[2:3], v[24:25], v[68:69], v[2:3] op_sel_hi:[1,0,1]
	s_nop 0
	v_pk_fma_f32 v[2:3], v[28:29], v[94:95], v[2:3] op_sel_hi:[1,0,1]
	v_mov_b32_e32 v28, v39
	v_pk_fma_f32 v[2:3], v[48:49], v[74:75], v[2:3] op_sel_hi:[1,0,1]
	s_waitcnt vmcnt(0)
	v_pk_fma_f32 v[6:7], v[34:35], v[28:29], v[6:7] op_sel_hi:[1,0,1]
	v_pk_fma_f32 v[2:3], v[54:55], v[10:11], v[2:3] op_sel_hi:[1,0,1]
	s_nop 0
	v_pk_fma_f32 v[2:3], v[58:59], v[76:77], v[2:3] op_sel_hi:[1,0,1]
	s_nop 0
	v_pk_fma_f32 v[2:3], v[62:63], v[14:15], v[2:3] op_sel_hi:[1,0,1]
	ds_read2_b32 v[14:15], v99 offset0:192 offset1:196
	ds_read2_b32 v[12:13], v99 offset0:200 offset1:204
	ds_read2_b32 v[10:11], v99 offset0:208 offset1:212
	ds_read2_b32 v[8:9], v99 offset0:216 offset1:220
	global_load_dwordx4 v[16:19], v[4:5], off nt
	v_add_co_u32_e32 v4, vcc, s68, v50
	v_pk_fma_f32 v[2:3], v[32:33], v[38:39], v[2:3] op_sel_hi:[1,0,1]
	s_nop 0
	v_addc_co_u32_e32 v5, vcc, 0, v51, vcc
	global_load_dwordx4 v[20:23], v[4:5], off offset:2048 nt
	v_add_co_u32_e32 v4, vcc, s69, v50
	v_pk_fma_f32 v[2:3], v[36:37], v[28:29], v[2:3] op_sel_hi:[1,0,1]
	s_nop 0
	v_addc_co_u32_e32 v5, vcc, 0, v51, vcc
	global_load_dwordx4 v[24:27], v[4:5], off nt
	v_add_co_u32_e32 v4, vcc, s70, v50
	s_waitcnt lgkmcnt(0)
	v_mov_b32_e32 v36, v9
	v_addc_co_u32_e32 v5, vcc, 0, v51, vcc
	global_load_dwordx4 v[46:49], v[4:5], off offset:2048 nt
	v_add_co_u32_e32 v4, vcc, s71, v50
	ds_read2_b32 v[30:31], v99 offset0:224 offset1:228
	s_nop 0
	v_addc_co_u32_e32 v5, vcc, 0, v51, vcc
	global_load_dwordx4 v[52:55], v[4:5], off nt
	v_add_co_u32_e32 v4, vcc, s72, v50
	s_waitcnt vmcnt(4)
	v_pk_fma_f32 v[2:3], v[18:19], v[40:41], v[2:3] op_sel_hi:[1,0,1]
	v_addc_co_u32_e32 v5, vcc, 0, v51, vcc
	global_load_dwordx4 v[56:59], v[4:5], off offset:2048 nt
	v_add_co_u32_e32 v4, vcc, s73, v50
	s_waitcnt vmcnt(4)
	v_pk_fma_f32 v[2:3], v[22:23], v[42:43], v[2:3] op_sel_hi:[1,0,1]
	v_addc_co_u32_e32 v5, vcc, 0, v51, vcc
	global_load_dwordx4 v[60:63], v[4:5], off nt
	v_add_co_u32_e32 v4, vcc, s74, v50
	s_waitcnt vmcnt(4)
	v_pk_fma_f32 v[2:3], v[26:27], v[14:15], v[2:3] op_sel_hi:[1,0,1]
	v_addc_co_u32_e32 v5, vcc, 0, v51, vcc
	global_load_dwordx4 v[64:67], v[4:5], off offset:2048 nt
	v_add_co_u32_e32 v4, vcc, s75, v50
	v_mov_b32_e32 v18, v15
	s_nop 0
	v_addc_co_u32_e32 v5, vcc, 0, v51, vcc
	global_load_dwordx4 v[68:71], v[4:5], off nt
	v_pk_fma_f32 v[6:7], v[16:17], v[40:41], v[6:7] op_sel_hi:[1,0,1]
	s_waitcnt vmcnt(5)
	v_pk_fma_f32 v[2:3], v[48:49], v[18:19], v[2:3] op_sel_hi:[1,0,1]
	v_pk_fma_f32 v[6:7], v[20:21], v[42:43], v[6:7] op_sel_hi:[1,0,1]
	s_waitcnt vmcnt(4)
	v_pk_fma_f32 v[2:3], v[54:55], v[12:13], v[2:3] op_sel_hi:[1,0,1]
	v_mov_b32_e32 v22, v13
	v_pk_fma_f32 v[6:7], v[24:25], v[14:15], v[6:7] op_sel_hi:[1,0,1]
	v_mov_b32_e32 v26, v11
	v_pk_fma_f32 v[6:7], v[46:47], v[18:19], v[6:7] op_sel_hi:[1,0,1]
	s_waitcnt vmcnt(3)
	v_pk_fma_f32 v[2:3], v[58:59], v[22:23], v[2:3] op_sel_hi:[1,0,1]
	v_pk_fma_f32 v[6:7], v[52:53], v[12:13], v[6:7] op_sel_hi:[1,0,1]
	s_waitcnt vmcnt(2)
	v_pk_fma_f32 v[2:3], v[62:63], v[10:11], v[2:3] op_sel_hi:[1,0,1]
	v_pk_fma_f32 v[6:7], v[56:57], v[22:23], v[6:7] op_sel_hi:[1,0,1]
	s_waitcnt vmcnt(1)
; template <int NB>
; __device__ __forceinline__ void sb_decode_task(const Params& P, float* lds, int task) {
;     ...
;     for (int vb = 0; vb < NBT; ++vb) {
;         if (vb + 1 < NBT) {
; #pragma unroll
;             for (int i = 0; i < NB; ++i) nx[i] = *(const float4*)(Vp + (size_t)(4 * NB * (vb + 1) + 4 * i + g) * (SH * HD)); }
; #pragma unroll
;         for (int i = 0; i < NB; ++i) { const float w = wl[4 * NB * vb + 4 * i + g]; o4.x += w * cur[i].x; o4.y += w * cur[i].y; o4.z += w * cur[i].z; o4.w += w * cur[i].w; }
; #pragma unroll
;         for (int i = 0; i < NB; ++i) cur[i] = nx[i];
;     }
; #pragma unroll
;     for (int off = 16; off < 64; off <<= 1) { o4.x += __shfl_xor(o4.x, off); o4.y += __shfl_xor(o4.y, off); o4.z += __shfl_xor(o4.z, off); o4.w += __shfl_xor(o4.w, off); }
;     if (g == 0) *(float4*)(dpart + (size_t)task * HD + 4 * c) = o4;
	v_pk_fma_f32 v[2:3], v[66:67], v[26:27], v[2:3] op_sel_hi:[1,0,1]
	v_pk_fma_f32 v[6:7], v[60:61], v[10:11], v[6:7] op_sel_hi:[1,0,1]
	v_and_b32_e32 v10, 64, v105
	v_pk_fma_f32 v[6:7], v[64:65], v[26:27], v[6:7] op_sel_hi:[1,0,1]
	v_add_u32_e32 v37, 64, v10
	v_xor_b32_e32 v10, 16, v105
	s_waitcnt vmcnt(0)
	v_pk_fma_f32 v[32:33], v[70:71], v[8:9], v[2:3] op_sel_hi:[1,0,1]
	v_add_co_u32_e32 v2, vcc, s80, v50
	v_pk_fma_f32 v[34:35], v[68:69], v[8:9], v[6:7] op_sel_hi:[1,0,1]
	s_nop 0
	v_addc_co_u32_e32 v3, vcc, 0, v51, vcc
	v_add_co_u32_e32 v6, vcc, s81, v50
	global_load_dwordx4 v[2:5], v[2:3], off offset:2048 nt
	s_nop 0
	v_addc_co_u32_e32 v7, vcc, 0, v51, vcc
	v_cmp_lt_i32_e32 vcc, v10, v37
	global_load_dwordx4 v[6:9], v[6:7], off nt
	ds_read2_b32 v[42:43], v99 offset0:232 offset1:236
	ds_read2_b32 v[40:41], v99 offset0:240 offset1:244
	ds_read2_b32 v[38:39], v99 offset0:248 offset1:252
	v_cndmask_b32_e32 v10, v105, v10, vcc
	v_lshlrev_b32_e32 v107, 2, v10
	v_add_co_u32_e32 v10, vcc, s82, v50
	s_waitcnt lgkmcnt(2)
	v_mov_b32_e32 v54, v43
	v_addc_co_u32_e32 v11, vcc, 0, v51, vcc
	v_add_co_u32_e32 v14, vcc, s83, v50
	global_load_dwordx4 v[10:13], v[10:11], off offset:2048 nt
	s_nop 0
	v_addc_co_u32_e32 v15, vcc, 0, v51, vcc
	v_add_co_u32_e32 v18, vcc, s84, v50
	global_load_dwordx4 v[14:17], v[14:15], off nt
	s_nop 0
	v_addc_co_u32_e32 v19, vcc, 0, v51, vcc
	v_add_co_u32_e32 v22, vcc, s85, v50
	global_load_dwordx4 v[18:21], v[18:19], off offset:2048 nt
	s_nop 0
	v_addc_co_u32_e32 v23, vcc, 0, v51, vcc
	v_add_co_u32_e32 v26, vcc, s86, v50
	global_load_dwordx4 v[22:25], v[22:23], off nt
	s_nop 0
	v_addc_co_u32_e32 v27, vcc, 0, v51, vcc
	v_add_co_u32_e32 v46, vcc, s87, v50
	global_load_dwordx4 v[26:29], v[26:27], off offset:2048 nt
	s_nop 0
	v_addc_co_u32_e32 v47, vcc, 0, v51, vcc
	v_add_co_u32_e32 v50, vcc, s88, v50
	global_load_dwordx4 v[46:49], v[46:47], off nt
	s_nop 0
	v_addc_co_u32_e32 v51, vcc, 0, v51, vcc
	global_load_dwordx4 v[50:53], v[50:51], off offset:2048 nt
	s_waitcnt lgkmcnt(1)
	v_mov_b32_e32 v56, v41
	s_waitcnt lgkmcnt(0)
	v_mov_b32_e32 v58, v39
	s_waitcnt vmcnt(8)
	v_pk_fma_f32 v[2:3], v[2:3], v[36:37], v[34:35] op_sel_hi:[1,0,1]
	v_mov_b32_e32 v34, v31
	v_pk_fma_f32 v[4:5], v[4:5], v[36:37], v[32:33] op_sel_hi:[1,0,1]
	s_waitcnt vmcnt(7)
	v_pk_fma_f32 v[2:3], v[6:7], v[30:31], v[2:3] op_sel_hi:[1,0,1]
	v_pk_fma_f32 v[4:5], v[8:9], v[30:31], v[4:5] op_sel_hi:[1,0,1]
	s_waitcnt vmcnt(6)
	v_pk_fma_f32 v[2:3], v[10:11], v[34:35], v[2:3] op_sel_hi:[1,0,1]
	v_pk_fma_f32 v[4:5], v[12:13], v[34:35], v[4:5] op_sel_hi:[1,0,1]
	ds_bpermute_b32 v10, v106, v44
	s_waitcnt vmcnt(5)
	v_pk_fma_f32 v[2:3], v[14:15], v[42:43], v[2:3] op_sel_hi:[1,0,1]
	v_pk_fma_f32 v[4:5], v[16:17], v[42:43], v[4:5] op_sel_hi:[1,0,1]
	s_waitcnt vmcnt(4)
	v_pk_fma_f32 v[2:3], v[18:19], v[54:55], v[2:3] op_sel_hi:[1,0,1]
	v_pk_fma_f32 v[4:5], v[20:21], v[54:55], v[4:5] op_sel_hi:[1,0,1]
	s_waitcnt vmcnt(3)
	v_pk_fma_f32 v[2:3], v[22:23], v[40:41], v[2:3] op_sel_hi:[1,0,1]
	v_pk_fma_f32 v[4:5], v[24:25], v[40:41], v[4:5] op_sel_hi:[1,0,1]
	s_waitcnt vmcnt(2)
	v_pk_fma_f32 v[2:3], v[26:27], v[56:57], v[2:3] op_sel_hi:[1,0,1]
	v_pk_fma_f32 v[4:5], v[28:29], v[56:57], v[4:5] op_sel_hi:[1,0,1]
	s_waitcnt vmcnt(1)
	v_pk_fma_f32 v[2:3], v[46:47], v[38:39], v[2:3] op_sel_hi:[1,0,1]
	v_pk_fma_f32 v[4:5], v[48:49], v[38:39], v[4:5] op_sel_hi:[1,0,1]
	s_waitcnt vmcnt(0)
	v_pk_fma_f32 v[2:3], v[50:51], v[58:59], v[2:3] op_sel_hi:[1,0,1]
	ds_bpermute_b32 v6, v107, v2
	ds_bpermute_b32 v7, v107, v3
	v_pk_fma_f32 v[4:5], v[52:53], v[58:59], v[4:5] op_sel_hi:[1,0,1]
	s_waitcnt lgkmcnt(0)
	v_pk_add_f32 v[2:3], v[2:3], v[6:7]
	ds_bpermute_b32 v6, v107, v4
	ds_bpermute_b32 v7, v107, v5
	s_waitcnt lgkmcnt(0)
	v_pk_add_f32 v[4:5], v[4:5], v[6:7]
	v_xor_b32_e32 v6, 32, v105
	v_cmp_lt_i32_e32 vcc, v6, v37
	s_nop 1
	v_cndmask_b32_e32 v6, v105, v6, vcc
	v_lshlrev_b32_e32 v114, 2, v6
	ds_bpermute_b32 v6, v114, v2
	ds_bpermute_b32 v7, v114, v3
	ds_bpermute_b32 v8, v114, v4
	ds_bpermute_b32 v9, v114, v5
	s_and_saveexec_b64 s[0:1], s[20:21]
	s_cbranch_execz .LBB0_1347
	s_ashr_i32 s35, s34, 31
	s_lshl_b64 s[36:37], s[34:35], 8
	v_lshl_add_u64 v[12:13], v[88:89], 0, s[36:37]
	s_waitcnt lgkmcnt(2)
	v_pk_add_f32 v[2:3], v[2:3], v[6:7]
	s_waitcnt lgkmcnt(0)
	v_pk_add_f32 v[4:5], v[4:5], v[8:9]
	global_store_dwordx4 v[12:13], v[2:5], off
